# RG-LRU gates: lane-uniform softplus of the decay parameter evaluated once per wave (lane=channel) and read back via LDS broadcast instead of 32x per lane (-736 VALU per wave item)
# baseline (speedup 1.0000x reference)
.Llru_tail:
	s_movk_i32 s0, 0x110
	v_ashrrev_i32_e32 v161, 6, v160
	v_and_b32_e32 v162, 31, v160
	v_mul_lo_u32 v33, v36, s0
	v_lshlrev_b32_e32 v34, 2, v37
	v_add3_u32 v33, s89, v33, v34
	v_lshl_or_b32 v163, v161, 5, v162
	s_waitcnt vmcnt(6)
	ds_write_b128 v33, v[4:7]
	ds_write_b128 v33, v[0:3] offset:16
	s_waitcnt vmcnt(4)
	ds_write_b128 v33, v[12:15] offset:32
	ds_write_b128 v33, v[8:11] offset:48
	s_waitcnt vmcnt(2)
	ds_write_b128 v33, v[20:23] offset:64
	ds_write_b128 v33, v[16:19] offset:80
	s_waitcnt vmcnt(0)
	ds_write_b128 v33, v[28:31] offset:96
	ds_write_b128 v33, v[24:27] offset:112
	v_mul_lo_u32 v0, v163, s0
	v_and_b32_e32 v1, 32, v160
	v_add3_u32 v64, s89, v0, v1
	s_waitcnt lgkmcnt(0)
	s_barrier
	ds_read_b128 v[0:3], v64
	ds_read_b128 v[4:7], v64 offset:16
	v_bfe_u32 v32, v160, 5, 1
	v_lshlrev_b32_e32 v168, 4, v32
	v_lshlrev_b32_e32 v100, 7, v162
	s_waitcnt lgkmcnt(1)
	v_cvt_pk_bf16_f32 v56, v0, v1
	v_cvt_pk_bf16_f32 v57, v2, v3
	s_waitcnt lgkmcnt(0)
	v_cvt_pk_bf16_f32 v58, v4, v5
	v_cvt_pk_bf16_f32 v59, v6, v7
	ds_read_b128 v[0:3], v64 offset:64
	ds_read_b128 v[4:7], v64 offset:80
	v_mov_b32_e32 v101, v169
	v_lshlrev_b32_e32 v164, 2, v32
	v_sub_u32_e32 v124, v64, v168
	s_waitcnt lgkmcnt(1)
	v_cvt_pk_bf16_f32 v52, v0, v1
	v_cvt_pk_bf16_f32 v53, v2, v3
	s_waitcnt lgkmcnt(0)
	v_cvt_pk_bf16_f32 v54, v4, v5
	v_cvt_pk_bf16_f32 v55, v6, v7
	ds_read_b128 v[0:3], v64 offset:128
	ds_read_b128 v[4:7], v64 offset:144
	s_waitcnt lgkmcnt(1)
	v_cvt_pk_bf16_f32 v48, v0, v1
	v_cvt_pk_bf16_f32 v49, v2, v3
	s_waitcnt lgkmcnt(0)
	v_cvt_pk_bf16_f32 v50, v4, v5
	v_cvt_pk_bf16_f32 v51, v6, v7
	ds_read_b128 v[0:3], v64 offset:192
	ds_read_b128 v[4:7], v64 offset:208
	s_load_dwordx2 s[6:7], s[54:55], 0x98
	s_load_dwordx4 s[0:3], s[54:55], 0xa8
	s_waitcnt lgkmcnt(0)
	v_cvt_pk_bf16_f32 v44, v0, v1
	s_add_u32 s5, s6, s60
	s_addc_u32 s6, s7, s61
	s_lshl_b32 s75, s74, 2
	s_add_u32 s10, s5, s75
	s_addc_u32 s11, s6, 0
	s_add_u32 s0, s0, s60
	s_addc_u32 s1, s1, s61
	s_add_u32 s12, s0, s75
	s_addc_u32 s13, s1, 0
	s_add_u32 s0, s2, s60
	s_addc_u32 s1, s3, s61
	s_add_u32 s8, s0, s75
	s_addc_u32 s9, s1, 0
	v_lshlrev_b32_e32 v176, 2, v191
	global_load_dword v170, v176, s[8:9]
	s_lshl_b32 s2, s4, 13
	s_add_u32 s0, s36, s2
	s_addc_u32 s1, s37, 0
	v_lshl_add_u64 v[96:97], s[0:1], 0, v[168:169]
	s_add_u32 s0, s38, s2
	s_addc_u32 s1, s39, 0
	v_lshl_add_u64 v[98:99], s[0:1], 0, v[168:169]
	v_lshl_add_u64 v[40:41], v[96:97], 0, v[100:101]
	v_cvt_pk_bf16_f32 v45, v2, v3
	v_cvt_pk_bf16_f32 v46, v4, v5
	v_cvt_pk_bf16_f32 v47, v6, v7
	v_lshl_add_u64 v[42:43], v[98:99], 0, v[100:101]
	global_load_dwordx4 v[0:3], v[40:41], off
	global_load_dwordx4 v[4:7], v[42:43], off
	global_load_dwordx4 v[32:35], v[40:41], off offset:32
	global_load_dwordx4 v[36:39], v[42:43], off offset:32
	s_mov_b32 s0, 0x3f317217
	s_mov_b32 s1, 0x7f800000
	s_mov_b32 s3, 0x3cf5c28f
	s_mov_b32 s2, 0xc1700000
	s_mov_b32 s4, 0xbdcccccd
	s_waitcnt vmcnt(3)
	v_mfma_f32_32x32x16_bf16 v[16:31], v[0:3], v[56:59], 0
	s_waitcnt vmcnt(2)
	v_mfma_f32_32x32x16_bf16 v[0:15], v[4:7], v[56:59], 0
	s_waitcnt vmcnt(1)
	v_mfma_f32_32x32x16_bf16 v[16:31], v[32:35], v[52:55], v[16:31]
	s_waitcnt vmcnt(0)
	v_mfma_f32_32x32x16_bf16 v[0:15], v[36:39], v[52:55], v[0:15]
	global_load_dwordx4 v[32:35], v[40:41], off offset:64
	global_load_dwordx4 v[36:39], v[42:43], off offset:64
	s_waitcnt vmcnt(1)
	v_mfma_f32_32x32x16_bf16 v[16:31], v[32:35], v[48:51], v[16:31]
	s_waitcnt vmcnt(0)
	v_mfma_f32_32x32x16_bf16 v[0:15], v[36:39], v[48:51], v[0:15]
	global_load_dwordx4 v[32:35], v[40:41], off offset:96
	global_load_dwordx4 v[36:39], v[42:43], off offset:96
	s_waitcnt vmcnt(1)
	v_mfma_f32_32x32x16_bf16 v[16:31], v[32:35], v[44:47], v[16:31]
	s_waitcnt vmcnt(0)
	v_mfma_f32_32x32x16_bf16 v[0:15], v[36:39], v[44:47], v[0:15]
	s_waitcnt vmcnt(0)
	v_mul_f32_e32 v171, 0xbfb8aa3b, v170
	v_exp_f32_e32 v171, v171
	s_nop 0
	v_add_f32_e32 v172, 1.0, v171
	v_cmp_gt_f32_e32 vcc, s28, v172
	s_nop 1
	v_cndmask_b32_e64 v173, 0, 32, vcc
	v_ldexp_f32 v172, v172, v173
	v_log_f32_e32 v172, v172
	s_nop 0
	v_mul_f32_e32 v173, 0x3f317217, v172
	v_fma_f32 v173, v172, s0, -v173
	v_fmac_f32_e32 v173, 0x3377d1cf, v172
	v_fmac_f32_e32 v173, 0x3f317217, v172
	v_cmp_lt_f32_e64 s[6:7], |v172|, s1
	s_nop 1
	v_cndmask_b32_e64 v172, v172, v173, s[6:7]
	v_cndmask_b32_e32 v173, 0, v201, vcc
	v_sub_f32_e32 v172, v172, v173
	v_fmamk_f32 v173, v171, 0xbe800000, v188
	v_fma_f32 v173, -v171, v173, 0.5
	v_fma_f32 v173, -v171, v173, 1.0
	v_mul_f32_e32 v173, v171, v173
	v_cmp_gt_f32_e64 s[6:7], s3, v171
	v_cmp_gt_f32_e32 vcc, s2, v170
	s_nop 0
	v_cndmask_b32_e64 v171, v172, v173, s[6:7]
	v_cndmask_b32_e64 v171, v171, -v170, vcc
	v_lshl_add_u32 v176, v161, 8, s89
	v_add_u32_e32 v176, 0x12000, v176
	v_lshl_add_u32 v180, v191, 2, v176
	ds_write_b32 v180, v171
	v_bfe_u32 v181, v160, 5, 1
	v_lshl_add_u32 v190, v181, 4, v176
	global_load_dwordx4 v[40:43], v168, s[10:11]
	global_load_dwordx4 v[36:39], v168, s[12:13]
	ds_read_b128 v[60:63], v190
	ds_read_b128 v[64:67], v124
	ds_read_b128 v[32:35], v124 offset:32
	s_waitcnt vmcnt(1)
	s_nop 3
	v_add_f32_e32 v16, v16, v40
	s_waitcnt vmcnt(0)
	v_add_f32_e32 v0, v0, v36
	s_waitcnt vmcnt(0)
	v_mul_f32_e32 v16, 0xbfb8aa3b, v16
	v_exp_f32_e32 v16, v16
	v_mul_f32_e32 v0, 0xbfb8aa3b, v0
	v_add_f32_e32 v16, 1.0, v16
	v_rcp_f32_e32 v16, v16
	s_nop 0
	v_mul_f32_e32 v16, 0xc1000000, v16
	v_exp_f32_e32 v0, v0
	v_add_f32_e32 v1, v1, v37
	v_add_f32_e32 v0, 1.0, v0
	v_rcp_f32_e32 v0, v0
	s_waitcnt lgkmcnt(1)
	v_mul_f32_e32 v0, v64, v0
	s_waitcnt lgkmcnt(0)
	v_mul_f32_e32 v16, v16, v60
	v_mul_f32_e32 v36, 0x3fb8aa3b, v16
	v_add_f32_e32 v16, v16, v16
	v_mul_f32_e32 v40, 0x3fb8aa3b, v16
	v_exp_f32_e32 v136, v36
	v_fmamk_f32 v36, v16, 0x3c088889, v189
	v_exp_f32_e32 v40, v40
	v_fmaak_f32 v36, v16, v36, 0x3e2aaaab
	v_fma_f32 v36, v16, v36, 0.5
	v_fma_f32 v36, v16, v36, 1.0
	v_mul_f32_e64 v36, v36, -v16
	v_sub_f32_e32 v40, 1.0, v40
	v_cmp_lt_f32_e32 vcc, s4, v16
	v_mul_f32_e32 v1, 0xbfb8aa3b, v1
	v_exp_f32_e32 v1, v1
	v_cndmask_b32_e32 v16, v40, v36, vcc
	v_sqrt_f32_e32 v16, v16
	v_add_f32_e32 v1, 1.0, v1
	v_rcp_f32_e32 v1, v1
	v_mul_f32_e32 v137, v0, v16
	v_add_f32_e32 v0, v17, v41
	v_mul_f32_e32 v0, 0xbfb8aa3b, v0
	v_exp_f32_e32 v0, v0
	v_mul_f32_e32 v1, v65, v1
	v_add_f32_e32 v0, 1.0, v0
	v_rcp_f32_e32 v0, v0
	s_nop 0
	v_mul_f32_e32 v0, 0xc1000000, v0
	s_nop 0
	s_nop 0
	v_mul_f32_e32 v0, v0, v61
	v_mul_f32_e32 v16, 0x3fb8aa3b, v0
	v_add_f32_e32 v0, v0, v0
	v_mul_f32_e32 v17, 0x3fb8aa3b, v0
	v_exp_f32_e32 v138, v16
	v_fmamk_f32 v16, v0, 0x3c088889, v189
	v_exp_f32_e32 v17, v17
	v_fmaak_f32 v16, v0, v16, 0x3e2aaaab
	v_fma_f32 v16, v0, v16, 0.5
	v_fma_f32 v16, v0, v16, 1.0
	v_mul_f32_e64 v16, v16, -v0
	v_sub_f32_e32 v17, 1.0, v17
	v_cmp_lt_f32_e32 vcc, s4, v0
	s_nop 1
	v_cndmask_b32_e32 v0, v17, v16, vcc
	v_sqrt_f32_e32 v0, v0
	s_nop 0
	v_mul_f32_e32 v139, v1, v0
	v_add_f32_e32 v1, v2, v38
	v_add_f32_e32 v0, v18, v42
	v_mul_f32_e32 v0, 0xbfb8aa3b, v0
	v_exp_f32_e32 v0, v0
	v_mul_f32_e32 v1, 0xbfb8aa3b, v1
	v_add_f32_e32 v0, 1.0, v0
	v_rcp_f32_e32 v0, v0
	v_exp_f32_e32 v1, v1
	v_mul_f32_e32 v0, 0xc1000000, v0
	v_add_f32_e32 v1, 1.0, v1
	v_rcp_f32_e32 v1, v1
	v_mul_f32_e32 v0, v0, v62
	v_mul_f32_e32 v2, 0x3fb8aa3b, v0
	v_add_f32_e32 v0, v0, v0
	v_mul_f32_e32 v16, 0x3fb8aa3b, v0
	v_exp_f32_e32 v140, v2
	v_fmamk_f32 v2, v0, 0x3c088889, v189
	v_exp_f32_e32 v16, v16
	v_fmaak_f32 v2, v0, v2, 0x3e2aaaab
	v_fma_f32 v2, v0, v2, 0.5
	v_fma_f32 v2, v0, v2, 1.0
	v_mul_f32_e64 v2, v2, -v0
	v_sub_f32_e32 v16, 1.0, v16
	v_cmp_lt_f32_e32 vcc, s4, v0
	v_mul_f32_e32 v1, v66, v1
	s_nop 0
	v_cndmask_b32_e32 v0, v16, v2, vcc
	v_sqrt_f32_e32 v0, v0
	s_nop 0
	v_mul_f32_e32 v141, v1, v0
	v_add_f32_e32 v1, v3, v39
	v_add_f32_e32 v0, v19, v43
	v_mul_f32_e32 v0, 0xbfb8aa3b, v0
	v_exp_f32_e32 v0, v0
	v_mul_f32_e32 v1, 0xbfb8aa3b, v1
	v_exp_f32_e32 v1, v1
	v_add_f32_e32 v0, 1.0, v0
	v_rcp_f32_e32 v0, v0
	s_nop 0
	v_mul_f32_e32 v0, 0xc1000000, v0
	v_mul_f32_e32 v0, v0, v63
	v_mul_f32_e32 v2, 0x3fb8aa3b, v0
	v_add_f32_e32 v0, v0, v0
	v_mul_f32_e32 v3, 0x3fb8aa3b, v0
	v_exp_f32_e32 v142, v2
	v_fmamk_f32 v2, v0, 0x3c088889, v189
	v_exp_f32_e32 v3, v3
	v_fmaak_f32 v2, v0, v2, 0x3e2aaaab
	v_fma_f32 v2, v0, v2, 0.5
	v_fma_f32 v2, v0, v2, 1.0
	v_add_f32_e32 v1, 1.0, v1
	v_mul_f32_e64 v2, v2, -v0
	v_sub_f32_e32 v3, 1.0, v3
	v_cmp_lt_f32_e32 vcc, s4, v0
	v_rcp_f32_e32 v1, v1
	s_nop 0
	v_cndmask_b32_e32 v0, v3, v2, vcc
	v_sqrt_f32_e32 v0, v0
	v_mul_f32_e32 v1, v67, v1
	v_mul_f32_e32 v143, v1, v0
	global_load_dwordx4 v[36:39], v168, s[10:11] offset:32
	global_load_dwordx4 v[16:19], v168, s[12:13] offset:32
	ds_read_b128 v[0:3], v190 offset:32
	s_waitcnt vmcnt(1)
	v_add_f32_e32 v20, v20, v36
	v_mul_f32_e32 v20, 0xbfb8aa3b, v20
	v_exp_f32_e32 v20, v20
	s_waitcnt vmcnt(0)
	v_add_f32_e32 v4, v4, v16
	v_mul_f32_e32 v4, 0xbfb8aa3b, v4
	v_exp_f32_e32 v4, v4
	v_add_f32_e32 v20, 1.0, v20
	s_waitcnt vmcnt(0)
	v_rcp_f32_e32 v20, v20
	v_add_f32_e32 v4, 1.0, v4
	v_rcp_f32_e32 v60, v4
	v_mul_f32_e32 v4, 0xc1000000, v20
	s_nop 1
	s_nop 0
	s_nop 1
	s_nop 0
	s_waitcnt lgkmcnt(0)
	v_mul_f32_e32 v0, v4, v0
	v_mul_f32_e32 v4, 0x3fb8aa3b, v0
	v_add_f32_e32 v0, v0, v0
	v_mul_f32_e32 v16, 0x3fb8aa3b, v0
	v_exp_f32_e32 v62, v4
	v_fmamk_f32 v4, v0, 0x3c088889, v189
	v_exp_f32_e32 v16, v16
	v_fmaak_f32 v4, v0, v4, 0x3e2aaaab
	v_fma_f32 v4, v0, v4, 0.5
	v_fma_f32 v4, v0, v4, 1.0
	v_mul_f32_e64 v4, v4, -v0
	v_sub_f32_e32 v16, 1.0, v16
	v_cmp_lt_f32_e32 vcc, s4, v0
	s_nop 1
	v_cndmask_b32_e32 v0, v16, v4, vcc
	v_add_f32_e32 v4, v5, v17
	v_mul_f32_e32 v4, 0xbfb8aa3b, v4
	v_exp_f32_e32 v4, v4
	v_sqrt_f32_e32 v64, v0
	v_add_f32_e32 v0, v21, v37
	v_mul_f32_e32 v0, 0xbfb8aa3b, v0
	v_add_f32_e32 v4, 1.0, v4
	v_rcp_f32_e32 v61, v4
	v_exp_f32_e32 v0, v0
	s_nop 0
	v_add_f32_e32 v0, 1.0, v0
	v_rcp_f32_e32 v0, v0
	s_nop 0
	v_mul_f32_e32 v0, 0xc1000000, v0
	s_nop 1
	s_nop 0
	v_mul_f32_e32 v0, v0, v1
	v_mul_f32_e32 v1, 0x3fb8aa3b, v0
	v_add_f32_e32 v0, v0, v0
	v_mul_f32_e32 v4, 0x3fb8aa3b, v0
	v_exp_f32_e32 v63, v1
	v_fmamk_f32 v1, v0, 0x3c088889, v189
	v_exp_f32_e32 v4, v4
	v_fmaak_f32 v1, v0, v1, 0x3e2aaaab
	v_fma_f32 v1, v0, v1, 0.5
	v_fma_f32 v1, v0, v1, 1.0
	v_mul_f32_e64 v1, v1, -v0
	v_sub_f32_e32 v4, 1.0, v4
	v_cmp_lt_f32_e32 vcc, s4, v0
	s_nop 1
	v_cndmask_b32_e32 v0, v4, v1, vcc
	v_add_f32_e32 v1, v6, v18
	v_mul_f32_e32 v1, 0xbfb8aa3b, v1
	v_exp_f32_e32 v1, v1
	v_sqrt_f32_e32 v65, v0
	v_add_f32_e32 v0, v22, v38
	v_mul_f32_e32 v0, 0xbfb8aa3b, v0
	v_add_f32_e32 v1, 1.0, v1
	v_rcp_f32_e32 v66, v1
	v_exp_f32_e32 v0, v0
	s_nop 0
	v_add_f32_e32 v0, 1.0, v0
	v_rcp_f32_e32 v0, v0
	s_nop 0
	v_mul_f32_e32 v0, 0xc1000000, v0
	s_nop 1
	s_nop 0
	v_mul_f32_e32 v0, v0, v2
	v_mul_f32_e32 v1, 0x3fb8aa3b, v0
	v_add_f32_e32 v0, v0, v0
	v_mul_f32_e32 v2, 0x3fb8aa3b, v0
	v_exp_f32_e32 v68, v1
	v_fmamk_f32 v1, v0, 0x3c088889, v189
	v_exp_f32_e32 v2, v2
	v_fmaak_f32 v1, v0, v1, 0x3e2aaaab
	v_fma_f32 v1, v0, v1, 0.5
	v_fma_f32 v1, v0, v1, 1.0
	v_mul_f32_e64 v1, v1, -v0
	v_sub_f32_e32 v2, 1.0, v2
	v_cmp_lt_f32_e32 vcc, s4, v0
	s_nop 1
	v_cndmask_b32_e32 v0, v2, v1, vcc
	v_add_f32_e32 v1, v7, v19
	v_mul_f32_e32 v1, 0xbfb8aa3b, v1
	v_exp_f32_e32 v1, v1
	v_sqrt_f32_e32 v70, v0
	v_add_f32_e32 v0, v23, v39
	v_mul_f32_e32 v0, 0xbfb8aa3b, v0
	v_add_f32_e32 v1, 1.0, v1
	v_rcp_f32_e32 v67, v1
	v_exp_f32_e32 v0, v0
	s_nop 0
	v_add_f32_e32 v0, 1.0, v0
	v_rcp_f32_e32 v0, v0
	s_nop 0
	v_mul_f32_e32 v0, 0xc1000000, v0
	s_nop 1
	s_nop 0
	v_mul_f32_e32 v0, v0, v3
	v_mul_f32_e32 v1, 0x3fb8aa3b, v0
	v_add_f32_e32 v0, v0, v0
	v_mul_f32_e32 v2, 0x3fb8aa3b, v0
	v_exp_f32_e32 v69, v1
	v_fmamk_f32 v1, v0, 0x3c088889, v189
	v_exp_f32_e32 v2, v2
	v_fmaak_f32 v1, v0, v1, 0x3e2aaaab
	v_fma_f32 v1, v0, v1, 0.5
	v_fma_f32 v1, v0, v1, 1.0
	v_mul_f32_e64 v1, v1, -v0
	v_sub_f32_e32 v2, 1.0, v2
	v_cmp_lt_f32_e32 vcc, s4, v0
	s_nop 1
	v_cndmask_b32_e32 v0, v2, v1, vcc
	v_sqrt_f32_e32 v71, v0
	global_load_dwordx4 v[0:3], v168, s[10:11] offset:64
	global_load_dwordx4 v[4:7], v168, s[12:13] offset:64
	ds_read_b128 v[16:19], v190 offset:64
	ds_read_b128 v[36:39], v124 offset:64
	s_waitcnt vmcnt(1)
	v_add_f32_e32 v0, v24, v0
	s_waitcnt vmcnt(0)
	v_add_f32_e32 v4, v8, v4
	v_mul_f32_e32 v4, 0xbfb8aa3b, v4
	v_exp_f32_e32 v4, v4
	v_mul_f32_e32 v0, 0xbfb8aa3b, v0
	v_exp_f32_e32 v0, v0
	v_add_f32_e32 v4, 1.0, v4
	v_rcp_f32_e32 v72, v4
	s_waitcnt vmcnt(0)
	v_add_f32_e32 v0, 1.0, v0
	v_rcp_f32_e32 v0, v0
	s_nop 0
	v_mul_f32_e32 v0, 0xc1000000, v0
	s_nop 0
	s_nop 0
	s_nop 1
	s_nop 0
	s_waitcnt lgkmcnt(0)
	v_mul_f32_e32 v0, v0, v16
	v_mul_f32_e32 v4, 0x3fb8aa3b, v0
	v_add_f32_e32 v0, v0, v0
	v_mul_f32_e32 v8, 0x3fb8aa3b, v0
	v_exp_f32_e32 v76, v4
	v_fmamk_f32 v4, v0, 0x3c088889, v189
	v_exp_f32_e32 v8, v8
	v_fmaak_f32 v4, v0, v4, 0x3e2aaaab
	v_fma_f32 v4, v0, v4, 0.5
	v_fma_f32 v4, v0, v4, 1.0
	v_mul_f32_e64 v4, v4, -v0
	v_sub_f32_e32 v8, 1.0, v8
	v_cmp_lt_f32_e32 vcc, s4, v0
	s_nop 1
	v_cndmask_b32_e32 v0, v8, v4, vcc
	v_sqrt_f32_e32 v80, v0
	v_add_f32_e32 v0, v25, v1
	v_add_f32_e32 v1, v9, v5
	v_mul_f32_e32 v1, 0xbfb8aa3b, v1
	v_exp_f32_e32 v1, v1
	v_mul_f32_e32 v0, 0xbfb8aa3b, v0
	v_exp_f32_e32 v0, v0
	v_add_f32_e32 v1, 1.0, v1
	v_rcp_f32_e32 v73, v1
	v_add_f32_e32 v0, 1.0, v0
	v_rcp_f32_e32 v0, v0
	s_nop 0
	v_mul_f32_e32 v0, 0xc1000000, v0
	s_nop 0
	s_nop 0
	s_nop 1
	s_nop 0
	v_mul_f32_e32 v0, v0, v17
	v_mul_f32_e32 v1, 0x3fb8aa3b, v0
	v_add_f32_e32 v0, v0, v0
	v_mul_f32_e32 v4, 0x3fb8aa3b, v0
	v_exp_f32_e32 v77, v1
	v_fmamk_f32 v1, v0, 0x3c088889, v189
	v_exp_f32_e32 v4, v4
	v_fmaak_f32 v1, v0, v1, 0x3e2aaaab
	v_fma_f32 v1, v0, v1, 0.5
	v_fma_f32 v1, v0, v1, 1.0
	v_mul_f32_e64 v1, v1, -v0
	v_sub_f32_e32 v4, 1.0, v4
	v_cmp_lt_f32_e32 vcc, s4, v0
	s_nop 1
	v_cndmask_b32_e32 v0, v4, v1, vcc
	v_add_f32_e32 v1, v10, v6
	v_mul_f32_e32 v1, 0xbfb8aa3b, v1
	v_exp_f32_e32 v1, v1
	v_sqrt_f32_e32 v81, v0
	v_add_f32_e32 v0, v26, v2
	v_mul_f32_e32 v0, 0xbfb8aa3b, v0
	v_add_f32_e32 v1, 1.0, v1
	v_rcp_f32_e32 v74, v1
	v_exp_f32_e32 v0, v0
	s_nop 0
	v_add_f32_e32 v0, 1.0, v0
	v_rcp_f32_e32 v0, v0
	s_nop 0
	v_mul_f32_e32 v0, 0xc1000000, v0
	s_nop 1
	s_nop 0
	v_mul_f32_e32 v0, v0, v18
	v_mul_f32_e32 v1, 0x3fb8aa3b, v0
	v_add_f32_e32 v0, v0, v0
	v_mul_f32_e32 v2, 0x3fb8aa3b, v0
	v_exp_f32_e32 v78, v1
	v_fmamk_f32 v1, v0, 0x3c088889, v189
	v_exp_f32_e32 v2, v2
	v_fmaak_f32 v1, v0, v1, 0x3e2aaaab
	v_fma_f32 v1, v0, v1, 0.5
	v_fma_f32 v1, v0, v1, 1.0
	v_mul_f32_e64 v1, v1, -v0
	v_sub_f32_e32 v2, 1.0, v2
	v_cmp_lt_f32_e32 vcc, s4, v0
	s_nop 1
	v_cndmask_b32_e32 v0, v2, v1, vcc
	v_add_f32_e32 v1, v11, v7
	v_mul_f32_e32 v1, 0xbfb8aa3b, v1
	v_exp_f32_e32 v1, v1
	v_sqrt_f32_e32 v82, v0
	v_add_f32_e32 v0, v27, v3
	v_mul_f32_e32 v0, 0xbfb8aa3b, v0
	v_add_f32_e32 v1, 1.0, v1
	v_rcp_f32_e32 v75, v1
	v_exp_f32_e32 v0, v0
	s_nop 0
	v_add_f32_e32 v0, 1.0, v0
	v_rcp_f32_e32 v0, v0
	s_nop 0
	v_mul_f32_e32 v0, 0xc1000000, v0
	s_nop 1
	s_nop 0
	v_mul_f32_e32 v0, v0, v19
	v_mul_f32_e32 v1, 0x3fb8aa3b, v0
	v_add_f32_e32 v0, v0, v0
	v_mul_f32_e32 v2, 0x3fb8aa3b, v0
	v_exp_f32_e32 v79, v1
	v_fmamk_f32 v1, v0, 0x3c088889, v189
	v_exp_f32_e32 v2, v2
	v_fmaak_f32 v1, v0, v1, 0x3e2aaaab
	v_fma_f32 v1, v0, v1, 0.5
	v_fma_f32 v1, v0, v1, 1.0
	v_mul_f32_e64 v1, v1, -v0
	v_sub_f32_e32 v2, 1.0, v2
	v_cmp_lt_f32_e32 vcc, s4, v0
	s_nop 1
	v_cndmask_b32_e32 v0, v2, v1, vcc
	v_sqrt_f32_e32 v83, v0
	global_load_dwordx4 v[4:7], v168, s[10:11] offset:96
	global_load_dwordx4 v[0:3], v168, s[12:13] offset:96
	ds_read_b128 v[8:11], v190 offset:96
	ds_read_b128 v[40:43], v124 offset:96
	s_waitcnt vmcnt(1)
	v_add_f32_e32 v4, v28, v4
	v_mul_f32_e32 v4, 0xbfb8aa3b, v4
	v_exp_f32_e32 v4, v4
	s_waitcnt vmcnt(0)
	v_add_f32_e32 v0, v12, v0
	v_mul_f32_e32 v0, 0xbfb8aa3b, v0
	v_exp_f32_e32 v0, v0
	v_add_f32_e32 v4, 1.0, v4
	v_rcp_f32_e32 v4, v4
	v_add_f32_e32 v1, v13, v1
	v_add_f32_e32 v0, 1.0, v0
	v_rcp_f32_e32 v84, v0
	v_mul_f32_e32 v0, 0xc1000000, v4
	s_waitcnt vmcnt(0)
	v_mul_f32_e32 v1, 0xbfb8aa3b, v1
	v_exp_f32_e32 v1, v1
	s_nop 0
	v_add_f32_e32 v1, 1.0, v1
	v_rcp_f32_e32 v85, v1
	s_nop 1
	s_nop 0
	s_waitcnt lgkmcnt(0)
	v_mul_f32_e32 v0, v0, v8
	v_mul_f32_e32 v4, 0x3fb8aa3b, v0
	v_add_f32_e32 v0, v0, v0
	v_mul_f32_e32 v8, 0x3fb8aa3b, v0
	v_exp_f32_e32 v86, v4
	v_fmamk_f32 v4, v0, 0x3c088889, v189
	v_exp_f32_e32 v8, v8
	v_fmaak_f32 v4, v0, v4, 0x3e2aaaab
	v_fma_f32 v4, v0, v4, 0.5
	v_fma_f32 v4, v0, v4, 1.0
	v_mul_f32_e64 v4, v4, -v0
	v_sub_f32_e32 v8, 1.0, v8
	v_cmp_lt_f32_e32 vcc, s4, v0
	s_nop 1
	v_cndmask_b32_e32 v0, v8, v4, vcc
	v_sqrt_f32_e32 v88, v0
	v_add_f32_e32 v0, v29, v5
	v_mul_f32_e32 v0, 0xbfb8aa3b, v0
	v_exp_f32_e32 v0, v0
	s_nop 0
	v_add_f32_e32 v0, 1.0, v0
	v_rcp_f32_e32 v0, v0
	s_nop 0
	v_mul_f32_e32 v0, 0xc1000000, v0
	v_mul_f32_e32 v0, v0, v9
	v_mul_f32_e32 v1, 0x3fb8aa3b, v0
	v_add_f32_e32 v0, v0, v0
	v_mul_f32_e32 v4, 0x3fb8aa3b, v0
	v_exp_f32_e32 v87, v1
	v_fmamk_f32 v1, v0, 0x3c088889, v189
	v_exp_f32_e32 v4, v4
	v_fmaak_f32 v1, v0, v1, 0x3e2aaaab
	v_fma_f32 v1, v0, v1, 0.5
	v_fma_f32 v1, v0, v1, 1.0
	v_mul_f32_e64 v1, v1, -v0
	v_sub_f32_e32 v4, 1.0, v4
	v_cmp_lt_f32_e32 vcc, s4, v0
	s_nop 1
	v_cndmask_b32_e32 v0, v4, v1, vcc
	v_add_f32_e32 v1, v14, v2
	v_mul_f32_e32 v1, 0xbfb8aa3b, v1
	v_exp_f32_e32 v1, v1
	v_sqrt_f32_e32 v89, v0
	v_add_f32_e32 v0, v30, v6
	v_mul_f32_e32 v0, 0xbfb8aa3b, v0
	v_add_f32_e32 v1, 1.0, v1
	v_rcp_f32_e32 v90, v1
	v_exp_f32_e32 v0, v0
	s_nop 0
	v_add_f32_e32 v0, 1.0, v0
	v_rcp_f32_e32 v0, v0
	s_nop 0
	v_mul_f32_e32 v0, 0xc1000000, v0
	s_nop 1
	s_nop 0
	v_mul_f32_e32 v0, v0, v10
	v_mul_f32_e32 v1, 0x3fb8aa3b, v0
	v_add_f32_e32 v0, v0, v0
	v_mul_f32_e32 v2, 0x3fb8aa3b, v0
	v_exp_f32_e32 v92, v1
	v_fmamk_f32 v1, v0, 0x3c088889, v189
	v_exp_f32_e32 v2, v2
	v_fmaak_f32 v1, v0, v1, 0x3e2aaaab
	v_fma_f32 v1, v0, v1, 0.5
	v_fma_f32 v1, v0, v1, 1.0
	v_mul_f32_e64 v1, v1, -v0
	v_sub_f32_e32 v2, 1.0, v2
	v_cmp_lt_f32_e32 vcc, s4, v0
	s_nop 1
	v_cndmask_b32_e32 v0, v2, v1, vcc
	v_add_f32_e32 v1, v15, v3
	v_mul_f32_e32 v1, 0xbfb8aa3b, v1
	v_exp_f32_e32 v1, v1
	v_sqrt_f32_e32 v94, v0
	v_add_f32_e32 v0, v31, v7
	v_mul_f32_e32 v0, 0xbfb8aa3b, v0
	v_add_f32_e32 v1, 1.0, v1
	v_rcp_f32_e32 v91, v1
	v_exp_f32_e32 v0, v0
	s_nop 0
	v_add_f32_e32 v0, 1.0, v0
	v_rcp_f32_e32 v0, v0
	s_nop 0
	v_mul_f32_e32 v0, 0xc1000000, v0
	s_nop 1
	s_nop 0
	v_mul_f32_e32 v0, v0, v11
	v_mul_f32_e32 v1, 0x3fb8aa3b, v0
	v_add_f32_e32 v0, v0, v0
	v_mul_f32_e32 v2, 0x3fb8aa3b, v0
	v_exp_f32_e32 v93, v1
	v_fmamk_f32 v1, v0, 0x3c088889, v189
	v_exp_f32_e32 v2, v2
	v_fmaak_f32 v1, v0, v1, 0x3e2aaaab
	v_fma_f32 v1, v0, v1, 0.5
	v_fma_f32 v1, v0, v1, 1.0
	v_mul_f32_e64 v1, v1, -v0
	v_sub_f32_e32 v2, 1.0, v2
	v_cmp_lt_f32_e32 vcc, s4, v0
	s_nop 1
	v_cndmask_b32_e32 v0, v2, v1, vcc
	v_sqrt_f32_e32 v95, v0
	v_or_b32_e32 v0, 0x1000, v100
	v_mov_b32_e32 v1, v169
	v_lshl_add_u64 v[100:101], v[96:97], 0, v[0:1]
	v_lshl_add_u64 v[102:103], v[98:99], 0, v[0:1]
	global_load_dwordx4 v[0:3], v[100:101], off
	global_load_dwordx4 v[4:7], v[102:103], off
	s_waitcnt vmcnt(1)
	v_mfma_f32_32x32x16_bf16 v[16:31], v[0:3], v[56:59], 0
	s_waitcnt vmcnt(0)
	v_mfma_f32_32x32x16_bf16 v[0:15], v[4:7], v[56:59], 0
	global_load_dwordx4 v[56:59], v[100:101], off offset:32
	global_load_dwordx4 v[96:99], v[102:103], off offset:32
	s_waitcnt vmcnt(1)
	v_mfma_f32_32x32x16_bf16 v[16:31], v[56:59], v[52:55], v[16:31]
	s_waitcnt vmcnt(0)
	v_mfma_f32_32x32x16_bf16 v[0:15], v[96:99], v[52:55], v[0:15]
	global_load_dwordx4 v[52:55], v[100:101], off offset:64
	global_load_dwordx4 v[56:59], v[102:103], off offset:64
	s_waitcnt vmcnt(1)
	v_mfma_f32_32x32x16_bf16 v[16:31], v[52:55], v[48:51], v[16:31]
	s_waitcnt vmcnt(0)
	v_mfma_f32_32x32x16_bf16 v[0:15], v[56:59], v[48:51], v[0:15]
	global_load_dwordx4 v[48:51], v[100:101], off offset:96
	global_load_dwordx4 v[52:55], v[102:103], off offset:96
	s_waitcnt vmcnt(0)
	v_mfma_f32_32x32x16_bf16 v[0:15], v[52:55], v[44:47], v[0:15]
	global_load_dwordx4 v[52:55], v168, s[10:11] offset:128
	global_load_dwordx4 v[56:59], v168, s[12:13] offset:128
	ds_read_b128 v[96:99], v190 offset:128
	s_waitcnt vmcnt(0)
	s_nop 7
	v_add_f32_e32 v0, v0, v56
	v_mfma_f32_32x32x16_bf16 v[16:31], v[48:51], v[44:47], v[16:31]
	v_mul_f32_e32 v0, 0xbfb8aa3b, v0
	v_exp_f32_e32 v0, v0
	v_add_f32_e32 v1, v1, v57
	v_mul_f32_e32 v1, 0xbfb8aa3b, v1
	v_exp_f32_e32 v1, v1
	v_add_f32_e32 v0, 1.0, v0
	v_rcp_f32_e32 v56, v0
	s_nop 4
	v_add_f32_e32 v16, v16, v52
	v_mul_f32_e32 v16, 0xbfb8aa3b, v16
	v_exp_f32_e32 v16, v16
	v_add_f32_e32 v1, 1.0, v1
	v_rcp_f32_e32 v57, v1
	s_waitcnt vmcnt(0)
	v_add_f32_e32 v16, 1.0, v16
	v_rcp_f32_e32 v16, v16
	ds_read_b128 v[48:51], v124 offset:128
	ds_read_b128 v[44:47], v124 offset:160
	v_mul_f32_e32 v0, 0xc1000000, v16
	s_nop 0
	s_nop 1
	s_nop 0
	s_nop 1
	s_nop 0
	s_waitcnt lgkmcnt(0)
	v_mul_f32_e32 v0, v0, v96
	v_mul_f32_e32 v16, 0x3fb8aa3b, v0
	v_add_f32_e32 v0, v0, v0
	v_mul_f32_e32 v52, 0x3fb8aa3b, v0
	v_exp_f32_e32 v96, v16
	v_fmamk_f32 v16, v0, 0x3c088889, v189
	v_exp_f32_e32 v52, v52
	v_fmaak_f32 v16, v0, v16, 0x3e2aaaab
	v_fma_f32 v16, v0, v16, 0.5
	v_fma_f32 v16, v0, v16, 1.0
	v_mul_f32_e64 v16, v16, -v0
	v_sub_f32_e32 v52, 1.0, v52
	v_cmp_lt_f32_e32 vcc, s4, v0
	s_nop 1
	v_cndmask_b32_e32 v0, v52, v16, vcc
	v_sqrt_f32_e32 v100, v0
	v_add_f32_e32 v0, v17, v53
	v_mul_f32_e32 v0, 0xbfb8aa3b, v0
	v_exp_f32_e32 v0, v0
	s_nop 0
	v_add_f32_e32 v0, 1.0, v0
	v_rcp_f32_e32 v0, v0
	s_nop 0
	v_mul_f32_e32 v0, 0xc1000000, v0
	v_mul_f32_e32 v0, v0, v97
	v_mul_f32_e32 v1, 0x3fb8aa3b, v0
	v_add_f32_e32 v0, v0, v0
	v_mul_f32_e32 v16, 0x3fb8aa3b, v0
	v_exp_f32_e32 v97, v1
	v_fmamk_f32 v1, v0, 0x3c088889, v189
	v_exp_f32_e32 v16, v16
	v_fmaak_f32 v1, v0, v1, 0x3e2aaaab
	v_fma_f32 v1, v0, v1, 0.5
	v_fma_f32 v1, v0, v1, 1.0
	v_mul_f32_e64 v1, v1, -v0
	v_sub_f32_e32 v16, 1.0, v16
	v_cmp_lt_f32_e32 vcc, s4, v0
	s_nop 1
	v_cndmask_b32_e32 v0, v16, v1, vcc
	v_add_f32_e32 v1, v2, v58
	v_mul_f32_e32 v1, 0xbfb8aa3b, v1
	v_exp_f32_e32 v1, v1
	v_sqrt_f32_e32 v101, v0
	v_add_f32_e32 v0, v18, v54
	v_mul_f32_e32 v0, 0xbfb8aa3b, v0
	v_add_f32_e32 v1, 1.0, v1
	v_rcp_f32_e32 v58, v1
	v_exp_f32_e32 v0, v0
	s_nop 0
	v_add_f32_e32 v0, 1.0, v0
	v_rcp_f32_e32 v0, v0
	s_nop 0
	v_mul_f32_e32 v0, 0xc1000000, v0
	s_nop 1
	s_nop 0
	v_mul_f32_e32 v0, v0, v98
	v_mul_f32_e32 v1, 0x3fb8aa3b, v0
	v_add_f32_e32 v0, v0, v0
	v_mul_f32_e32 v2, 0x3fb8aa3b, v0
	v_exp_f32_e32 v98, v1
	v_fmamk_f32 v1, v0, 0x3c088889, v189
	v_exp_f32_e32 v2, v2
	v_fmaak_f32 v1, v0, v1, 0x3e2aaaab
	v_fma_f32 v1, v0, v1, 0.5
	v_fma_f32 v1, v0, v1, 1.0
	v_mul_f32_e64 v1, v1, -v0
	v_sub_f32_e32 v2, 1.0, v2
	v_cmp_lt_f32_e32 vcc, s4, v0
	s_nop 1
	v_cndmask_b32_e32 v0, v2, v1, vcc
	v_add_f32_e32 v1, v3, v59
	v_mul_f32_e32 v1, 0xbfb8aa3b, v1
	v_exp_f32_e32 v1, v1
	v_sqrt_f32_e32 v102, v0
	v_add_f32_e32 v0, v19, v55
	v_mul_f32_e32 v0, 0xbfb8aa3b, v0
	v_add_f32_e32 v1, 1.0, v1
	v_rcp_f32_e32 v59, v1
	v_exp_f32_e32 v0, v0
	s_nop 0
	v_add_f32_e32 v0, 1.0, v0
	v_rcp_f32_e32 v0, v0
	s_nop 0
	v_mul_f32_e32 v0, 0xc1000000, v0
	s_nop 1
	s_nop 0
	v_mul_f32_e32 v0, v0, v99
	v_mul_f32_e32 v1, 0x3fb8aa3b, v0
	v_add_f32_e32 v0, v0, v0
	v_mul_f32_e32 v2, 0x3fb8aa3b, v0
	v_exp_f32_e32 v99, v1
	v_fmamk_f32 v1, v0, 0x3c088889, v189
	v_exp_f32_e32 v2, v2
	v_fmaak_f32 v1, v0, v1, 0x3e2aaaab
	v_fma_f32 v1, v0, v1, 0.5
	v_fma_f32 v1, v0, v1, 1.0
	v_mul_f32_e64 v1, v1, -v0
	v_sub_f32_e32 v2, 1.0, v2
	v_cmp_lt_f32_e32 vcc, s4, v0
	s_nop 1
	v_cndmask_b32_e32 v0, v2, v1, vcc
	v_sqrt_f32_e32 v103, v0
	global_load_dwordx4 v[16:19], v168, s[10:11] offset:160
	global_load_dwordx4 v[0:3], v168, s[12:13] offset:160
	ds_read_b128 v[52:55], v190 offset:160
	s_waitcnt vmcnt(1)
	v_add_f32_e32 v16, v20, v16
	v_mul_f32_e32 v16, 0xbfb8aa3b, v16
	v_exp_f32_e32 v16, v16
	s_waitcnt vmcnt(0)
	v_add_f32_e32 v0, v4, v0
	v_mul_f32_e32 v0, 0xbfb8aa3b, v0
	v_exp_f32_e32 v0, v0
	v_add_f32_e32 v16, 1.0, v16
	s_waitcnt vmcnt(0)
	v_rcp_f32_e32 v16, v16
	v_add_f32_e32 v0, 1.0, v0
	v_rcp_f32_e32 v104, v0
	v_mul_f32_e32 v0, 0xc1000000, v16
	v_add_f32_e32 v1, v5, v1
	v_mul_f32_e32 v1, 0xbfb8aa3b, v1
	v_exp_f32_e32 v1, v1
	s_nop 0
	v_add_f32_e32 v1, 1.0, v1
	v_rcp_f32_e32 v105, v1
	s_waitcnt lgkmcnt(0)
	v_mul_f32_e32 v0, v0, v52
	v_mul_f32_e32 v4, 0x3fb8aa3b, v0
	v_add_f32_e32 v0, v0, v0
	v_mul_f32_e32 v16, 0x3fb8aa3b, v0
	v_exp_f32_e32 v52, v4
	v_fmamk_f32 v4, v0, 0x3c088889, v189
	v_exp_f32_e32 v16, v16
	v_fmaak_f32 v4, v0, v4, 0x3e2aaaab
	v_fma_f32 v4, v0, v4, 0.5
	v_fma_f32 v4, v0, v4, 1.0
	v_mul_f32_e64 v4, v4, -v0
	v_sub_f32_e32 v16, 1.0, v16
	v_cmp_lt_f32_e32 vcc, s4, v0
	s_nop 1
	v_cndmask_b32_e32 v0, v16, v4, vcc
	v_sqrt_f32_e32 v106, v0
	v_add_f32_e32 v0, v21, v17
	v_mul_f32_e32 v0, 0xbfb8aa3b, v0
	v_exp_f32_e32 v0, v0
	s_nop 0
	v_add_f32_e32 v0, 1.0, v0
	v_rcp_f32_e32 v0, v0
	s_nop 0
	v_mul_f32_e32 v0, 0xc1000000, v0
	v_mul_f32_e32 v0, v0, v53
	v_mul_f32_e32 v1, 0x3fb8aa3b, v0
	v_add_f32_e32 v0, v0, v0
	v_mul_f32_e32 v4, 0x3fb8aa3b, v0
	v_exp_f32_e32 v53, v1
	v_fmamk_f32 v1, v0, 0x3c088889, v189
	v_exp_f32_e32 v4, v4
	v_fmaak_f32 v1, v0, v1, 0x3e2aaaab
	v_fma_f32 v1, v0, v1, 0.5
	v_fma_f32 v1, v0, v1, 1.0
	v_mul_f32_e64 v1, v1, -v0
	v_sub_f32_e32 v4, 1.0, v4
	v_cmp_lt_f32_e32 vcc, s4, v0
	s_nop 1
	v_cndmask_b32_e32 v0, v4, v1, vcc
	v_add_f32_e32 v1, v6, v2
	v_mul_f32_e32 v1, 0xbfb8aa3b, v1
	v_exp_f32_e32 v1, v1
	v_sqrt_f32_e32 v107, v0
	v_add_f32_e32 v0, v22, v18
	v_mul_f32_e32 v0, 0xbfb8aa3b, v0
	v_add_f32_e32 v1, 1.0, v1
	v_rcp_f32_e32 v108, v1
	v_exp_f32_e32 v0, v0
	s_nop 0
	v_add_f32_e32 v0, 1.0, v0
	v_rcp_f32_e32 v0, v0
	s_nop 0
	v_mul_f32_e32 v0, 0xc1000000, v0
	s_nop 1
	s_nop 0
	v_mul_f32_e32 v0, v0, v54
	v_mul_f32_e32 v1, 0x3fb8aa3b, v0
	v_add_f32_e32 v0, v0, v0
	v_mul_f32_e32 v2, 0x3fb8aa3b, v0
	v_exp_f32_e32 v54, v1
	v_fmamk_f32 v1, v0, 0x3c088889, v189
	v_exp_f32_e32 v2, v2
	v_fmaak_f32 v1, v0, v1, 0x3e2aaaab
	v_fma_f32 v1, v0, v1, 0.5
	v_fma_f32 v1, v0, v1, 1.0
	v_mul_f32_e64 v1, v1, -v0
	v_sub_f32_e32 v2, 1.0, v2
	v_cmp_lt_f32_e32 vcc, s4, v0
	s_nop 1
	v_cndmask_b32_e32 v0, v2, v1, vcc
	v_sqrt_f32_e32 v110, v0
	v_add_f32_e32 v0, v23, v19
	v_add_f32_e32 v1, v7, v3
	global_load_dwordx4 v[4:7], v168, s[10:11] offset:192
	global_load_dwordx4 v[16:19], v168, s[12:13] offset:192
	ds_read_b128 v[20:23], v190 offset:192
	v_mul_f32_e32 v1, 0xbfb8aa3b, v1
	v_exp_f32_e32 v1, v1
	v_mul_f32_e32 v0, 0xbfb8aa3b, v0
	v_exp_f32_e32 v0, v0
	v_add_f32_e32 v1, 1.0, v1
	v_rcp_f32_e32 v109, v1
	v_add_f32_e32 v0, 1.0, v0
	v_rcp_f32_e32 v0, v0
	s_nop 0
	v_mul_f32_e32 v0, 0xc1000000, v0
	s_waitcnt vmcnt(1)
	v_add_f32_e32 v4, v24, v4
	s_waitcnt vmcnt(0)
	v_add_f32_e32 v8, v8, v16
	v_mul_f32_e32 v8, 0xbfb8aa3b, v8
	v_exp_f32_e32 v8, v8
	s_nop 0
	v_add_f32_e32 v8, 1.0, v8
	v_rcp_f32_e32 v112, v8
	s_waitcnt vmcnt(0)
	v_mul_f32_e32 v0, v0, v55
	v_mul_f32_e32 v1, 0x3fb8aa3b, v0
	v_add_f32_e32 v0, v0, v0
	v_mul_f32_e32 v2, 0x3fb8aa3b, v0
	v_exp_f32_e32 v55, v1
	v_fmamk_f32 v1, v0, 0x3c088889, v189
	v_exp_f32_e32 v2, v2
	v_fmaak_f32 v1, v0, v1, 0x3e2aaaab
	v_fma_f32 v1, v0, v1, 0.5
	v_fma_f32 v1, v0, v1, 1.0
	v_mul_f32_e64 v1, v1, -v0
	v_sub_f32_e32 v2, 1.0, v2
	v_cmp_lt_f32_e32 vcc, s4, v0
	v_mul_f32_e32 v4, 0xbfb8aa3b, v4
	s_nop 0
	v_cndmask_b32_e32 v0, v2, v1, vcc
	v_exp_f32_e32 v4, v4
	v_sqrt_f32_e32 v111, v0
	v_add_f32_e32 v4, 1.0, v4
	v_rcp_f32_e32 v4, v4
	ds_read_b128 v[0:3], v124 offset:192
	v_mul_f32_e32 v4, 0xc1000000, v4
	s_nop 0
	s_nop 0
	s_waitcnt lgkmcnt(0)
	v_mul_f32_e32 v4, v4, v20
	v_mul_f32_e32 v8, 0x3fb8aa3b, v4
	v_add_f32_e32 v4, v4, v4
	v_mul_f32_e32 v16, 0x3fb8aa3b, v4
	v_exp_f32_e32 v116, v8
	v_fmamk_f32 v8, v4, 0x3c088889, v189
	v_exp_f32_e32 v16, v16
	v_fmaak_f32 v8, v4, v8, 0x3e2aaaab
	v_fma_f32 v8, v4, v8, 0.5
	v_fma_f32 v8, v4, v8, 1.0
	v_mul_f32_e64 v8, v8, -v4
	v_sub_f32_e32 v16, 1.0, v16
	v_cmp_lt_f32_e32 vcc, s4, v4
	s_nop 1
	v_cndmask_b32_e32 v4, v16, v8, vcc
	v_sqrt_f32_e32 v120, v4
	v_add_f32_e32 v4, v25, v5
	v_add_f32_e32 v5, v9, v17
	v_mul_f32_e32 v5, 0xbfb8aa3b, v5
	v_exp_f32_e32 v5, v5
	v_mul_f32_e32 v4, 0xbfb8aa3b, v4
	v_exp_f32_e32 v4, v4
	v_add_f32_e32 v5, 1.0, v5
	v_rcp_f32_e32 v113, v5
	v_add_f32_e32 v4, 1.0, v4
	v_rcp_f32_e32 v4, v4
	s_nop 0
	v_mul_f32_e32 v4, 0xc1000000, v4
	s_nop 0
	s_nop 0
	s_nop 1
	s_nop 0
	v_mul_f32_e32 v4, v4, v21
	v_mul_f32_e32 v5, 0x3fb8aa3b, v4
	v_add_f32_e32 v4, v4, v4
	v_mul_f32_e32 v8, 0x3fb8aa3b, v4
	v_exp_f32_e32 v117, v5
	v_fmamk_f32 v5, v4, 0x3c088889, v189
	v_exp_f32_e32 v8, v8
	v_fmaak_f32 v5, v4, v5, 0x3e2aaaab
	v_fma_f32 v5, v4, v5, 0.5
	v_fma_f32 v5, v4, v5, 1.0
	v_mul_f32_e64 v5, v5, -v4
	v_sub_f32_e32 v8, 1.0, v8
	v_cmp_lt_f32_e32 vcc, s4, v4
	s_nop 1
	v_cndmask_b32_e32 v4, v8, v5, vcc
	v_add_f32_e32 v5, v10, v18
	v_mul_f32_e32 v5, 0xbfb8aa3b, v5
	v_exp_f32_e32 v5, v5
	v_sqrt_f32_e32 v121, v4
	v_add_f32_e32 v4, v26, v6
	v_mul_f32_e32 v4, 0xbfb8aa3b, v4
	v_add_f32_e32 v5, 1.0, v5
	v_rcp_f32_e32 v114, v5
	v_exp_f32_e32 v4, v4
	s_nop 0
	v_add_f32_e32 v4, 1.0, v4
	v_rcp_f32_e32 v4, v4
	s_nop 0
	v_mul_f32_e32 v4, 0xc1000000, v4
	s_nop 1
	s_nop 0
	v_mul_f32_e32 v4, v4, v22
	v_mul_f32_e32 v5, 0x3fb8aa3b, v4
	v_add_f32_e32 v4, v4, v4
	v_mul_f32_e32 v6, 0x3fb8aa3b, v4
	v_exp_f32_e32 v118, v5
	v_fmamk_f32 v5, v4, 0x3c088889, v189
	v_exp_f32_e32 v6, v6
	v_fmaak_f32 v5, v4, v5, 0x3e2aaaab
	v_fma_f32 v5, v4, v5, 0.5
	v_fma_f32 v5, v4, v5, 1.0
	v_mul_f32_e64 v5, v5, -v4
	v_sub_f32_e32 v6, 1.0, v6
	v_cmp_lt_f32_e32 vcc, s4, v4
	s_nop 1
	v_cndmask_b32_e32 v4, v6, v5, vcc
	v_add_f32_e32 v5, v11, v19
	v_mul_f32_e32 v5, 0xbfb8aa3b, v5
	v_exp_f32_e32 v5, v5
	v_sqrt_f32_e32 v122, v4
	v_add_f32_e32 v4, v27, v7
	v_mul_f32_e32 v4, 0xbfb8aa3b, v4
	v_add_f32_e32 v5, 1.0, v5
	v_rcp_f32_e32 v115, v5
	v_exp_f32_e32 v4, v4
	s_nop 0
	v_add_f32_e32 v4, 1.0, v4
	v_rcp_f32_e32 v4, v4
	s_nop 0
	v_mul_f32_e32 v4, 0xc1000000, v4
	s_nop 1
	s_nop 0
	v_mov_b32_e32 v5, v23
	global_load_dwordx4 v[20:23], v168, s[10:11] offset:224
	global_load_dwordx4 v[16:19], v168, s[12:13] offset:224
	ds_read_b128 v[8:11], v190 offset:224
	v_mul_f32_e32 v4, v4, v5
	v_mul_f32_e32 v5, 0x3fb8aa3b, v4
	v_add_f32_e32 v4, v4, v4
	v_mul_f32_e32 v6, 0x3fb8aa3b, v4
	v_exp_f32_e32 v119, v5
	v_fmamk_f32 v5, v4, 0x3c088889, v189
	v_exp_f32_e32 v6, v6
	v_fmaak_f32 v5, v4, v5, 0x3e2aaaab
	v_fma_f32 v5, v4, v5, 0.5
	v_fma_f32 v5, v4, v5, 1.0
	v_mul_f32_e64 v5, v5, -v4
	v_sub_f32_e32 v6, 1.0, v6
	v_cmp_lt_f32_e32 vcc, s4, v4
	s_waitcnt vmcnt(1)
	v_add_f32_e32 v20, v28, v20
	v_mul_f32_e32 v20, 0xbfb8aa3b, v20
	v_exp_f32_e32 v20, v20
	s_waitcnt vmcnt(0)
	v_add_f32_e32 v12, v12, v16
	v_mul_f32_e32 v12, 0xbfb8aa3b, v12
	v_exp_f32_e32 v12, v12
	v_add_f32_e32 v20, 1.0, v20
	s_waitcnt vmcnt(0)
	v_rcp_f32_e32 v20, v20
	v_cndmask_b32_e32 v4, v6, v5, vcc
	v_add_f32_e32 v12, 1.0, v12
	v_sqrt_f32_e32 v123, v4
	ds_read_b128 v[4:7], v124 offset:224
	v_rcp_f32_e32 v124, v12
	v_mul_f32_e32 v12, 0xc1000000, v20
	s_nop 1
	s_nop 0
	s_nop 1
	s_nop 0
	s_waitcnt lgkmcnt(0)
	v_mul_f32_e32 v8, v12, v8
	v_mul_f32_e32 v12, 0x3fb8aa3b, v8
	v_add_f32_e32 v8, v8, v8
	v_mul_f32_e32 v16, 0x3fb8aa3b, v8
	v_exp_f32_e32 v126, v12
	v_fmamk_f32 v12, v8, 0x3c088889, v189
	v_exp_f32_e32 v16, v16
	v_fmaak_f32 v12, v8, v12, 0x3e2aaaab
	v_fma_f32 v12, v8, v12, 0.5
	v_fma_f32 v12, v8, v12, 1.0
	v_mul_f32_e64 v12, v12, -v8
	v_sub_f32_e32 v16, 1.0, v16
	v_cmp_lt_f32_e32 vcc, s4, v8
	s_nop 1
	v_cndmask_b32_e32 v8, v16, v12, vcc
	v_add_f32_e32 v12, v13, v17
	v_mul_f32_e32 v12, 0xbfb8aa3b, v12
	v_exp_f32_e32 v12, v12
	v_sqrt_f32_e32 v128, v8
	v_add_f32_e32 v8, v29, v21
	v_mul_f32_e32 v8, 0xbfb8aa3b, v8
	v_add_f32_e32 v12, 1.0, v12
	v_rcp_f32_e32 v125, v12
	v_exp_f32_e32 v8, v8
	s_nop 0
	v_add_f32_e32 v8, 1.0, v8
	v_rcp_f32_e32 v8, v8
	s_nop 0
	v_mul_f32_e32 v8, 0xc1000000, v8
	s_nop 1
	s_nop 0
	v_mul_f32_e32 v8, v8, v9
	v_mul_f32_e32 v9, 0x3fb8aa3b, v8
	v_add_f32_e32 v8, v8, v8
	v_mul_f32_e32 v12, 0x3fb8aa3b, v8
	v_exp_f32_e32 v127, v9
	v_fmamk_f32 v9, v8, 0x3c088889, v189
	v_exp_f32_e32 v12, v12
	v_fmaak_f32 v9, v8, v9, 0x3e2aaaab
	v_fma_f32 v9, v8, v9, 0.5
	v_fma_f32 v9, v8, v9, 1.0
	v_mul_f32_e64 v9, v9, -v8
	v_sub_f32_e32 v12, 1.0, v12
	v_cmp_lt_f32_e32 vcc, s4, v8
	s_nop 1
	v_cndmask_b32_e32 v8, v12, v9, vcc
	v_add_f32_e32 v9, v14, v18
	v_mul_f32_e32 v9, 0xbfb8aa3b, v9
	v_exp_f32_e32 v9, v9
	v_sqrt_f32_e32 v129, v8
	v_add_f32_e32 v8, v30, v22
	v_mul_f32_e32 v8, 0xbfb8aa3b, v8
	v_add_f32_e32 v9, 1.0, v9
	v_rcp_f32_e32 v130, v9
	v_exp_f32_e32 v8, v8
	s_nop 0
	v_add_f32_e32 v8, 1.0, v8
	v_rcp_f32_e32 v8, v8
	s_nop 0
	v_mul_f32_e32 v8, 0xc1000000, v8
	s_nop 1
	s_nop 0
	v_mul_f32_e32 v8, v8, v10
	v_mul_f32_e32 v9, 0x3fb8aa3b, v8
	v_add_f32_e32 v8, v8, v8
	v_mul_f32_e32 v10, 0x3fb8aa3b, v8
	v_exp_f32_e32 v132, v9
	v_fmamk_f32 v9, v8, 0x3c088889, v189
	v_exp_f32_e32 v10, v10
	v_fmaak_f32 v9, v8, v9, 0x3e2aaaab
	v_fma_f32 v9, v8, v9, 0.5
	v_fma_f32 v9, v8, v9, 1.0
	v_mul_f32_e64 v9, v9, -v8
	v_sub_f32_e32 v10, 1.0, v10
	v_cmp_lt_f32_e32 vcc, s4, v8
	s_nop 1
	v_cndmask_b32_e32 v8, v10, v9, vcc
	v_add_f32_e32 v9, v15, v19
	v_mul_f32_e32 v9, 0xbfb8aa3b, v9
	v_exp_f32_e32 v9, v9
	v_sqrt_f32_e32 v134, v8
	v_add_f32_e32 v8, v31, v23
	v_mul_f32_e32 v8, 0xbfb8aa3b, v8
	v_add_f32_e32 v9, 1.0, v9
	v_rcp_f32_e32 v131, v9
	v_exp_f32_e32 v8, v8
	s_nop 0
	v_add_f32_e32 v8, 1.0, v8
	v_rcp_f32_e32 v8, v8
	s_nop 0
	v_mul_f32_e32 v8, 0xc1000000, v8
	s_nop 1
	s_nop 0
	v_mul_f32_e32 v8, v8, v11
	v_mul_f32_e32 v9, 0x3fb8aa3b, v8
	v_add_f32_e32 v8, v8, v8
	v_mul_f32_e32 v10, 0x3fb8aa3b, v8
	v_exp_f32_e32 v133, v9
	v_fmamk_f32 v9, v8, 0x3c088889, v189
	v_exp_f32_e32 v10, v10
	v_fmaak_f32 v9, v8, v9, 0x3e2aaaab
	v_fma_f32 v9, v8, v9, 0.5
	v_fma_f32 v9, v8, v9, 1.0
	v_mul_f32_e64 v9, v9, -v8
	v_sub_f32_e32 v10, 1.0, v10
	v_cmp_lt_f32_e32 vcc, s4, v8
	s_nop 1
	v_cndmask_b32_e32 v8, v10, v9, vcc
	v_sqrt_f32_e32 v135, v8
	v_and_b32_e32 v8, 0x60, v191
	v_add_u32_e32 v9, -1, v191
	v_cmp_lt_i32_e32 vcc, v9, v8
	s_nop 1
	v_cndmask_b32_e32 v9, v9, v191, vcc
	v_and_b32_e32 v165, 15, v162
	v_mov_b32_dpp v10, v137 row_shr:1 row_mask:0xf bank_mask:0xf
	v_cmp_eq_u32_e32 vcc, 0, v165
	v_mov_b32_dpp v11, v139 row_shr:1 row_mask:0xf bank_mask:0xf
	v_mov_b32_dpp v9, v136 row_shr:1 row_mask:0xf bank_mask:0xf
	v_mov_b32_dpp v14, v68 row_shr:1 row_mask:0xf bank_mask:0xf
	s_waitcnt lgkmcnt(3)
	v_fma_f32 v10, v136, v10, v137
	v_cndmask_b32_e32 v12, v10, v137, vcc
	v_mov_b32_dpp v10, v138 row_shr:1 row_mask:0xf bank_mask:0xf
	s_waitcnt lgkmcnt(3)
	v_fma_f32 v11, v138, v11, v139
	v_cndmask_b32_e32 v16, v11, v139, vcc
	v_mov_b32_dpp v11, v141 row_shr:1 row_mask:0xf bank_mask:0xf
	v_mov_b32_dpp v15, v69 row_shr:1 row_mask:0xf bank_mask:0xf
	s_waitcnt lgkmcnt(2)
	v_mul_f32_e32 v10, v138, v10
	v_cndmask_b32_e32 v13, v10, v138, vcc
	v_mov_b32_dpp v10, v140 row_shr:1 row_mask:0xf bank_mask:0xf
	s_waitcnt lgkmcnt(2)
	v_fma_f32 v11, v140, v11, v141
	v_cndmask_b32_e32 v18, v11, v141, vcc
	v_mov_b32_dpp v11, v143 row_shr:1 row_mask:0xf bank_mask:0xf
	v_mul_f32_e32 v9, v136, v9
	s_waitcnt lgkmcnt(1)
	v_mul_f32_e32 v10, v140, v10
	v_cndmask_b32_e32 v17, v10, v140, vcc
	v_mov_b32_dpp v10, v142 row_shr:1 row_mask:0xf bank_mask:0xf
	s_waitcnt lgkmcnt(1)
	v_fma_f32 v11, v142, v11, v143
	v_cndmask_b32_e32 v20, v11, v143, vcc
	v_mov_b32_dpp v11, v63 row_shr:1 row_mask:0xf bank_mask:0xf
	v_cndmask_b32_e32 v9, v9, v136, vcc
	s_waitcnt lgkmcnt(1)
	v_mul_f32_e32 v10, v142, v10
	v_cndmask_b32_e32 v19, v10, v142, vcc
	v_mov_b32_dpp v10, v62 row_shr:1 row_mask:0xf bank_mask:0xf
	v_mov_b32_dpp v28, v76 row_shr:1 row_mask:0xf bank_mask:0xf
	v_mov_b32_dpp v29, v77 row_shr:1 row_mask:0xf bank_mask:0xf
	v_mov_b32_dpp v24, v78 row_shr:1 row_mask:0xf bank_mask:0xf
	v_mov_b32_dpp v25, v79 row_shr:1 row_mask:0xf bank_mask:0xf
	v_mov_b32_dpp v30, v86 row_shr:1 row_mask:0xf bank_mask:0xf
	v_mov_b32_dpp v31, v87 row_shr:1 row_mask:0xf bank_mask:0xf
	v_mov_b32_dpp v26, v92 row_shr:1 row_mask:0xf bank_mask:0xf
	v_mov_b32_dpp v27, v93 row_shr:1 row_mask:0xf bank_mask:0xf
	v_mov_b32_dpp v158, v96 row_shr:1 row_mask:0xf bank_mask:0xf
	v_mov_b32_dpp v159, v97 row_shr:1 row_mask:0xf bank_mask:0xf
	v_mov_b32_dpp v156, v98 row_shr:1 row_mask:0xf bank_mask:0xf
	v_mov_b32_dpp v157, v99 row_shr:1 row_mask:0xf bank_mask:0xf
	v_mov_b32_dpp v154, v52 row_shr:1 row_mask:0xf bank_mask:0xf
	v_mov_b32_dpp v155, v53 row_shr:1 row_mask:0xf bank_mask:0xf
	v_mov_b32_dpp v152, v54 row_shr:1 row_mask:0xf bank_mask:0xf
	v_mov_b32_dpp v153, v55 row_shr:1 row_mask:0xf bank_mask:0xf
	v_mov_b32_dpp v150, v116 row_shr:1 row_mask:0xf bank_mask:0xf
	v_mov_b32_dpp v151, v117 row_shr:1 row_mask:0xf bank_mask:0xf
	v_mov_b32_dpp v148, v118 row_shr:1 row_mask:0xf bank_mask:0xf
	v_mov_b32_dpp v149, v119 row_shr:1 row_mask:0xf bank_mask:0xf
	v_mov_b32_dpp v146, v126 row_shr:1 row_mask:0xf bank_mask:0xf
	v_mov_b32_dpp v147, v127 row_shr:1 row_mask:0xf bank_mask:0xf
	v_mov_b32_dpp v136, v132 row_shr:1 row_mask:0xf bank_mask:0xf
	v_mov_b32_dpp v137, v133 row_shr:1 row_mask:0xf bank_mask:0xf
	v_add_u32_e32 v21, -2, v191
	v_cmp_lt_i32_e64 s[6:7], v21, v8
	s_nop 1
	v_cndmask_b32_e64 v21, v21, v191, s[6:7]
	v_lshlrev_b32_e32 v166, 2, v21
	v_mov_b32_dpp v21, v9 row_shr:2 row_mask:0xf bank_mask:0xf
	v_mov_b32_dpp v22, v12 row_shr:2 row_mask:0xf bank_mask:0xf
	v_cmp_gt_u32_e64 s[6:7], 2, v165
	s_waitcnt lgkmcnt(1)
	v_mul_f32_e32 v21, v9, v21
	s_waitcnt lgkmcnt(0)
	v_fma_f32 v22, v9, v22, v12
	v_cndmask_b32_e64 v9, v21, v9, s[6:7]
	v_cndmask_b32_e64 v12, v22, v12, s[6:7]
	v_mov_b32_dpp v21, v13 row_shr:2 row_mask:0xf bank_mask:0xf
	v_mov_b32_dpp v22, v16 row_shr:2 row_mask:0xf bank_mask:0xf
	s_waitcnt lgkmcnt(1)
	v_mul_f32_e32 v21, v13, v21
	s_waitcnt lgkmcnt(0)
	v_fma_f32 v22, v13, v22, v16
	v_cndmask_b32_e64 v13, v21, v13, s[6:7]
	v_cndmask_b32_e64 v16, v22, v16, s[6:7]
	v_mov_b32_dpp v21, v17 row_shr:2 row_mask:0xf bank_mask:0xf
	v_mov_b32_dpp v22, v18 row_shr:2 row_mask:0xf bank_mask:0xf
	s_waitcnt lgkmcnt(1)
	v_mul_f32_e32 v21, v17, v21
	s_waitcnt lgkmcnt(0)
	v_fma_f32 v22, v17, v22, v18
	v_cndmask_b32_e64 v17, v21, v17, s[6:7]
	v_cndmask_b32_e64 v18, v22, v18, s[6:7]
	v_mov_b32_dpp v21, v19 row_shr:2 row_mask:0xf bank_mask:0xf
	v_mov_b32_dpp v22, v20 row_shr:2 row_mask:0xf bank_mask:0xf
	s_waitcnt lgkmcnt(1)
	v_mul_f32_e32 v21, v19, v21
	s_waitcnt lgkmcnt(0)
	v_fma_f32 v22, v19, v22, v20
	v_cndmask_b32_e64 v19, v21, v19, s[6:7]
	v_cndmask_b32_e64 v20, v22, v20, s[6:7]
	v_add_u32_e32 v21, -4, v191
	v_cmp_lt_i32_e64 s[8:9], v21, v8
	s_nop 1
	v_cndmask_b32_e64 v21, v21, v191, s[8:9]
	v_lshlrev_b32_e32 v167, 2, v21
	v_mov_b32_dpp v21, v9 row_shr:4 row_mask:0xf bank_mask:0xf
	v_mov_b32_dpp v22, v12 row_shr:4 row_mask:0xf bank_mask:0xf
	v_cmp_gt_u32_e64 s[8:9], 4, v165
	s_waitcnt lgkmcnt(1)
	v_mul_f32_e32 v21, v9, v21
	s_waitcnt lgkmcnt(0)
	v_fma_f32 v22, v9, v22, v12
	v_cndmask_b32_e64 v9, v21, v9, s[8:9]
	v_cndmask_b32_e64 v12, v22, v12, s[8:9]
	v_mov_b32_dpp v21, v13 row_shr:4 row_mask:0xf bank_mask:0xf
	v_mov_b32_dpp v22, v16 row_shr:4 row_mask:0xf bank_mask:0xf
	s_waitcnt lgkmcnt(1)
	v_mul_f32_e32 v21, v13, v21
	s_waitcnt lgkmcnt(0)
	v_fma_f32 v22, v13, v22, v16
	v_cndmask_b32_e64 v13, v21, v13, s[8:9]
	v_cndmask_b32_e64 v16, v22, v16, s[8:9]
	v_mov_b32_dpp v21, v17 row_shr:4 row_mask:0xf bank_mask:0xf
	v_mov_b32_dpp v22, v18 row_shr:4 row_mask:0xf bank_mask:0xf
	s_waitcnt lgkmcnt(1)
	v_mul_f32_e32 v21, v17, v21
	s_waitcnt lgkmcnt(0)
	v_fma_f32 v22, v17, v22, v18
	v_cndmask_b32_e64 v17, v21, v17, s[8:9]
	v_cndmask_b32_e64 v18, v22, v18, s[8:9]
	v_mov_b32_dpp v21, v19 row_shr:4 row_mask:0xf bank_mask:0xf
	v_mov_b32_dpp v22, v20 row_shr:4 row_mask:0xf bank_mask:0xf
	s_waitcnt lgkmcnt(1)
	v_mul_f32_e32 v21, v19, v21
	s_waitcnt lgkmcnt(0)
	v_fma_f32 v22, v19, v22, v20
	v_cndmask_b32_e64 v19, v21, v19, s[8:9]
	v_cndmask_b32_e64 v20, v22, v20, s[8:9]
	v_add_u32_e32 v21, -8, v191
	v_cmp_lt_i32_e64 s[10:11], v21, v8
	s_nop 1
	v_cndmask_b32_e64 v21, v21, v191, s[10:11]
	v_lshlrev_b32_e32 v168, 2, v21
	v_mov_b32_dpp v21, v9 row_shr:8 row_mask:0xf bank_mask:0xf
	v_mov_b32_dpp v22, v12 row_shr:8 row_mask:0xf bank_mask:0xf
	v_cmp_gt_u32_e64 s[10:11], 8, v165
	s_waitcnt lgkmcnt(1)
	v_mul_f32_e32 v21, v9, v21
	s_waitcnt lgkmcnt(0)
	v_fma_f32 v22, v9, v22, v12
	v_cndmask_b32_e64 v140, v21, v9, s[10:11]
	v_cndmask_b32_e64 v138, v22, v12, s[10:11]
	v_mov_b32_dpp v9, v13 row_shr:8 row_mask:0xf bank_mask:0xf
	v_mov_b32_dpp v12, v16 row_shr:8 row_mask:0xf bank_mask:0xf
	s_waitcnt lgkmcnt(1)
	v_mul_f32_e32 v9, v13, v9
	s_waitcnt lgkmcnt(0)
	v_fma_f32 v12, v13, v12, v16
	v_cndmask_b32_e64 v141, v9, v13, s[10:11]
	v_cndmask_b32_e64 v139, v12, v16, s[10:11]
	v_mov_b32_dpp v9, v17 row_shr:8 row_mask:0xf bank_mask:0xf
	v_mov_b32_dpp v12, v18 row_shr:8 row_mask:0xf bank_mask:0xf
	s_waitcnt lgkmcnt(1)
	v_mul_f32_e32 v9, v17, v9
	s_waitcnt lgkmcnt(0)
	v_fma_f32 v12, v17, v12, v18
	v_cndmask_b32_e64 v144, v9, v17, s[10:11]
	v_cndmask_b32_e64 v142, v12, v18, s[10:11]
	v_mov_b32_dpp v9, v19 row_shr:8 row_mask:0xf bank_mask:0xf
	v_mov_b32_dpp v12, v20 row_shr:8 row_mask:0xf bank_mask:0xf
	s_waitcnt lgkmcnt(1)
	v_mul_f32_e32 v9, v19, v9
	s_waitcnt lgkmcnt(0)
	v_fma_f32 v12, v19, v12, v20
	v_cndmask_b32_e64 v145, v9, v19, s[10:11]
	v_cndmask_b32_e64 v143, v12, v20, s[10:11]
	v_pk_mul_f32 v[12:13], v[32:33], v[60:61]
	v_add_u32_e32 v9, -16, v191
	v_pk_mul_f32 v[12:13], v[12:13], v[64:65]
	s_nop 1
	v_mov_b32_dpp v16, v12 row_shr:1 row_mask:0xf bank_mask:0xf
	v_mov_b32_dpp v17, v13 row_shr:1 row_mask:0xf bank_mask:0xf
	v_pk_mul_f32 v[10:11], v[62:63], v[10:11]
	v_cmp_lt_i32_e64 s[12:13], v9, v8
	v_cndmask_b32_e32 v11, v11, v63, vcc
	v_cndmask_b32_e32 v10, v10, v62, vcc
	s_waitcnt lgkmcnt(0)
	v_pk_fma_f32 v[16:17], v[62:63], v[16:17], v[12:13]
	v_cndmask_b32_e64 v8, v9, v191, s[12:13]
	v_cndmask_b32_e32 v17, v17, v13, vcc
	v_cndmask_b32_e32 v16, v16, v12, vcc
	v_mov_b32_dpp v20, v10 row_shr:2 row_mask:0xf bank_mask:0xf
	s_nop 1
	v_mov_b32_dpp v22, v16 row_shr:2 row_mask:0xf bank_mask:0xf
	v_mov_b32_dpp v21, v11 row_shr:2 row_mask:0xf bank_mask:0xf
	v_mov_b32_dpp v23, v17 row_shr:2 row_mask:0xf bank_mask:0xf
	v_lshlrev_b32_e32 v170, 2, v8
	v_mov_b32_dpp v18, v138 row_bcast:15 row_mask:0xa bank_mask:0xf
	v_mov_b32_dpp v19, v139 row_bcast:15 row_mask:0xa bank_mask:0xf
	s_waitcnt lgkmcnt(3)
	v_pk_mul_f32 v[20:21], v[10:11], v[20:21]
	s_waitcnt lgkmcnt(2)
	v_pk_fma_f32 v[22:23], v[10:11], v[22:23], v[16:17]
	v_cndmask_b32_e64 v21, v21, v11, s[6:7]
	v_cndmask_b32_e64 v20, v20, v10, s[6:7]
	v_cndmask_b32_e64 v17, v23, v17, s[6:7]
	v_cndmask_b32_e64 v16, v22, v16, s[6:7]
	s_waitcnt lgkmcnt(0)
	v_pk_fma_f32 v[12:13], v[140:141], v[18:19], v[138:139]
	v_mov_b32_dpp v18, v144 row_bcast:15 row_mask:0xa bank_mask:0xf
	v_mov_b32_dpp v19, v145 row_bcast:15 row_mask:0xa bank_mask:0xf
	v_mov_b32_dpp v22, v20 row_shr:4 row_mask:0xf bank_mask:0xf
	v_mov_b32_dpp v32, v16 row_shr:4 row_mask:0xf bank_mask:0xf
	v_mov_b32_dpp v23, v21 row_shr:4 row_mask:0xf bank_mask:0xf
	v_mov_b32_dpp v33, v17 row_shr:4 row_mask:0xf bank_mask:0xf
	s_waitcnt lgkmcnt(4)
	v_pk_mul_f32 v[10:11], v[144:145], v[18:19]
	v_pk_mul_f32 v[14:15], v[68:69], v[14:15]
	v_mov_b32_dpp v8, v140 row_bcast:15 row_mask:0xa bank_mask:0xf
	s_waitcnt lgkmcnt(2)
	v_pk_mul_f32 v[18:19], v[20:21], v[22:23]
	s_waitcnt lgkmcnt(1)
	v_pk_fma_f32 v[22:23], v[20:21], v[32:33], v[16:17]
	v_cndmask_b32_e64 v19, v19, v21, s[8:9]
	v_cndmask_b32_e64 v17, v23, v17, s[8:9]
	v_cndmask_b32_e64 v16, v22, v16, s[8:9]
	v_pk_mul_f32 v[22:23], v[34:35], v[66:67]
	v_cndmask_b32_e64 v18, v18, v20, s[8:9]
	v_pk_mul_f32 v[22:23], v[22:23], v[70:71]
	s_nop 1
	v_mov_b32_dpp v32, v22 row_shr:1 row_mask:0xf bank_mask:0xf
	v_mov_b32_dpp v33, v23 row_shr:1 row_mask:0xf bank_mask:0xf
	v_mov_b32_dpp v20, v18 row_shr:8 row_mask:0xf bank_mask:0xf
	v_mov_b32_dpp v21, v19 row_shr:8 row_mask:0xf bank_mask:0xf
	v_cndmask_b32_e32 v15, v15, v69, vcc
	v_cndmask_b32_e32 v14, v14, v68, vcc
	s_waitcnt lgkmcnt(2)
	v_pk_fma_f32 v[32:33], v[68:69], v[32:33], v[22:23]
	v_mov_b32_dpp v34, v16 row_shr:8 row_mask:0xf bank_mask:0xf
	v_cndmask_b32_e32 v23, v33, v23, vcc
	v_cndmask_b32_e32 v22, v32, v22, vcc
	v_mov_b32_dpp v35, v17 row_shr:8 row_mask:0xf bank_mask:0xf
	v_mov_b32_dpp v32, v14 row_shr:2 row_mask:0xf bank_mask:0xf
	v_mov_b32_dpp v62, v22 row_shr:2 row_mask:0xf bank_mask:0xf
	v_mov_b32_dpp v33, v15 row_shr:2 row_mask:0xf bank_mask:0xf
	v_mov_b32_dpp v63, v23 row_shr:2 row_mask:0xf bank_mask:0xf
	s_waitcnt lgkmcnt(6)
	v_pk_mul_f32 v[20:21], v[18:19], v[20:21]
	s_waitcnt lgkmcnt(4)
	v_pk_fma_f32 v[34:35], v[18:19], v[34:35], v[16:17]
	v_cndmask_b32_e64 v65, v21, v19, s[10:11]
	v_cndmask_b32_e64 v64, v20, v18, s[10:11]
	s_waitcnt lgkmcnt(1)
	v_pk_mul_f32 v[18:19], v[14:15], v[32:33]
	s_waitcnt lgkmcnt(0)
	v_pk_fma_f32 v[20:21], v[14:15], v[62:63], v[22:23]
	v_cndmask_b32_e64 v15, v19, v15, s[6:7]
	v_cndmask_b32_e64 v14, v18, v14, s[6:7]
	v_cndmask_b32_e64 v19, v21, v23, s[6:7]
	v_cndmask_b32_e64 v18, v20, v22, s[6:7]
	v_mov_b32_dpp v20, v14 row_shr:4 row_mask:0xf bank_mask:0xf
	s_nop 1
	v_mov_b32_dpp v22, v18 row_shr:4 row_mask:0xf bank_mask:0xf
	v_mov_b32_dpp v21, v15 row_shr:4 row_mask:0xf bank_mask:0xf
	v_mov_b32_dpp v23, v19 row_shr:4 row_mask:0xf bank_mask:0xf
	v_cndmask_b32_e64 v67, v35, v17, s[10:11]
	v_cndmask_b32_e64 v66, v34, v16, s[10:11]
	v_mov_b32_dpp v9, v141 row_bcast:15 row_mask:0xa bank_mask:0xf
	s_waitcnt lgkmcnt(2)
	v_pk_mul_f32 v[20:21], v[14:15], v[20:21]
	s_waitcnt lgkmcnt(1)
	v_pk_fma_f32 v[22:23], v[14:15], v[22:23], v[18:19]
	v_cndmask_b32_e64 v15, v21, v15, s[8:9]
	v_cndmask_b32_e64 v14, v20, v14, s[8:9]
	v_cndmask_b32_e64 v19, v23, v19, s[8:9]
	v_cndmask_b32_e64 v18, v22, v18, s[8:9]
	v_mov_b32_dpp v20, v14 row_shr:8 row_mask:0xf bank_mask:0xf
	s_nop 1
	v_mov_b32_dpp v22, v18 row_shr:8 row_mask:0xf bank_mask:0xf
	v_mov_b32_dpp v21, v15 row_shr:8 row_mask:0xf bank_mask:0xf
	v_mov_b32_dpp v23, v19 row_shr:8 row_mask:0xf bank_mask:0xf
	v_mov_b32_dpp v60, v142 row_bcast:15 row_mask:0xa bank_mask:0xf
	v_mov_b32_dpp v61, v143 row_bcast:15 row_mask:0xa bank_mask:0xf
	v_mov_b32_dpp v16, v64 row_bcast:15 row_mask:0xa bank_mask:0xf
	s_waitcnt lgkmcnt(4)
	v_pk_mul_f32 v[20:21], v[14:15], v[20:21]
	s_waitcnt lgkmcnt(3)
	v_pk_fma_f32 v[22:23], v[14:15], v[22:23], v[18:19]
	v_cndmask_b32_e64 v69, v21, v15, s[10:11]
	v_cndmask_b32_e64 v68, v20, v14, s[10:11]
	v_cndmask_b32_e64 v71, v23, v19, s[10:11]
	v_cndmask_b32_e64 v70, v22, v18, s[10:11]
	v_mov_b32_dpp v32, v66 row_bcast:15 row_mask:0xa bank_mask:0xf
	v_mov_b32_dpp v17, v65 row_bcast:15 row_mask:0xa bank_mask:0xf
	v_mov_b32_dpp v33, v67 row_bcast:15 row_mask:0xa bank_mask:0xf
	v_mov_b32_dpp v18, v68 row_bcast:15 row_mask:0xa bank_mask:0xf
	v_mov_b32_dpp v34, v70 row_bcast:15 row_mask:0xa bank_mask:0xf
	v_mov_b32_dpp v19, v69 row_bcast:15 row_mask:0xa bank_mask:0xf
	v_mov_b32_dpp v35, v71 row_bcast:15 row_mask:0xa bank_mask:0xf
	v_pk_mul_f32 v[8:9], v[140:141], v[8:9]
	s_waitcnt lgkmcnt(8)
	v_pk_fma_f32 v[14:15], v[144:145], v[60:61], v[142:143]
	s_waitcnt lgkmcnt(5)
	v_pk_mul_f32 v[20:21], v[64:65], v[16:17]
	s_waitcnt lgkmcnt(4)
	v_pk_fma_f32 v[16:17], v[64:65], v[32:33], v[66:67]
	s_waitcnt lgkmcnt(1)
	v_pk_mul_f32 v[22:23], v[68:69], v[18:19]
	s_waitcnt lgkmcnt(0)
	v_pk_fma_f32 v[18:19], v[68:69], v[34:35], v[70:71]
	v_pk_mul_f32 v[32:33], v[36:37], v[72:73]
	v_pk_mul_f32 v[28:29], v[76:77], v[28:29]
	v_pk_mul_f32 v[32:33], v[32:33], v[80:81]
	s_nop 1
	v_mov_b32_dpp v34, v32 row_shr:1 row_mask:0xf bank_mask:0xf
	v_mov_b32_dpp v35, v33 row_shr:1 row_mask:0xf bank_mask:0xf
	v_cndmask_b32_e32 v29, v29, v77, vcc
	v_cndmask_b32_e32 v28, v28, v76, vcc
	v_pk_mul_f32 v[38:39], v[38:39], v[74:75]
	v_pk_mul_f32 v[24:25], v[78:79], v[24:25]
	s_waitcnt lgkmcnt(0)
	v_pk_fma_f32 v[34:35], v[76:77], v[34:35], v[32:33]
	v_pk_mul_f32 v[38:39], v[38:39], v[82:83]
	v_cndmask_b32_e32 v33, v35, v33, vcc
	v_cndmask_b32_e32 v32, v34, v32, vcc
	v_mov_b32_dpp v34, v28 row_shr:2 row_mask:0xf bank_mask:0xf
	v_mov_b32_dpp v35, v29 row_shr:2 row_mask:0xf bank_mask:0xf
	v_mov_b32_dpp v36, v32 row_shr:2 row_mask:0xf bank_mask:0xf
	v_mov_b32_dpp v37, v33 row_shr:2 row_mask:0xf bank_mask:0xf
	v_mov_b32_dpp v60, v38 row_shr:1 row_mask:0xf bank_mask:0xf
	v_mov_b32_dpp v61, v39 row_shr:1 row_mask:0xf bank_mask:0xf
	s_waitcnt lgkmcnt(4)
	v_pk_mul_f32 v[34:35], v[28:29], v[34:35]
	v_cndmask_b32_e32 v25, v25, v79, vcc
	s_waitcnt lgkmcnt(2)
	v_pk_fma_f32 v[36:37], v[28:29], v[36:37], v[32:33]
	v_cndmask_b32_e64 v29, v35, v29, s[6:7]
	v_cndmask_b32_e64 v28, v34, v28, s[6:7]
	v_cndmask_b32_e64 v33, v37, v33, s[6:7]
	v_cndmask_b32_e64 v32, v36, v32, s[6:7]
	v_mov_b32_dpp v34, v28 row_shr:4 row_mask:0xf bank_mask:0xf
	v_mov_b32_dpp v35, v29 row_shr:4 row_mask:0xf bank_mask:0xf
	v_mov_b32_dpp v36, v32 row_shr:4 row_mask:0xf bank_mask:0xf
	v_mov_b32_dpp v37, v33 row_shr:4 row_mask:0xf bank_mask:0xf
	v_cndmask_b32_e32 v24, v24, v78, vcc
	v_pk_mul_f32 v[40:41], v[40:41], v[84:85]
	s_waitcnt lgkmcnt(2)
	v_pk_mul_f32 v[34:35], v[28:29], v[34:35]
	v_pk_mul_f32 v[40:41], v[40:41], v[88:89]
	s_waitcnt lgkmcnt(0)
	v_pk_fma_f32 v[36:37], v[28:29], v[36:37], v[32:33]
	v_cndmask_b32_e64 v29, v35, v29, s[8:9]
	v_cndmask_b32_e64 v28, v34, v28, s[8:9]
	s_nop 1
	v_mov_b32_dpp v34, v28 row_shr:8 row_mask:0xf bank_mask:0xf
	v_mov_b32_dpp v35, v29 row_shr:8 row_mask:0xf bank_mask:0xf
	v_cndmask_b32_e64 v33, v37, v33, s[8:9]
	v_cndmask_b32_e64 v32, v36, v32, s[8:9]
	s_nop 1
	v_mov_b32_dpp v36, v32 row_shr:8 row_mask:0xf bank_mask:0xf
	v_mov_b32_dpp v37, v33 row_shr:8 row_mask:0xf bank_mask:0xf
	s_waitcnt lgkmcnt(2)
	v_pk_mul_f32 v[34:35], v[28:29], v[34:35]
	v_pk_mul_f32 v[30:31], v[86:87], v[30:31]
	v_cndmask_b32_e64 v73, v35, v29, s[10:11]
	v_cndmask_b32_e64 v72, v34, v28, s[10:11]
	s_waitcnt lgkmcnt(0)
	v_pk_fma_f32 v[36:37], v[28:29], v[36:37], v[32:33]
	v_pk_fma_f32 v[28:29], v[78:79], v[60:61], v[38:39]
	v_mov_b32_dpp v34, v24 row_shr:2 row_mask:0xf bank_mask:0xf
	v_cndmask_b32_e32 v29, v29, v39, vcc
	v_cndmask_b32_e32 v28, v28, v38, vcc
	v_mov_b32_dpp v35, v25 row_shr:2 row_mask:0xf bank_mask:0xf
	s_nop 1
	v_mov_b32_dpp v38, v28 row_shr:2 row_mask:0xf bank_mask:0xf
	v_mov_b32_dpp v39, v29 row_shr:2 row_mask:0xf bank_mask:0xf
	v_cndmask_b32_e64 v75, v37, v33, s[10:11]
	v_cndmask_b32_e64 v74, v36, v32, s[10:11]
	s_waitcnt lgkmcnt(2)
	v_pk_mul_f32 v[34:35], v[24:25], v[34:35]
	v_mov_b32_dpp v32, v72 row_bcast:15 row_mask:0xa bank_mask:0xf
	s_waitcnt lgkmcnt(1)
	v_pk_fma_f32 v[36:37], v[24:25], v[38:39], v[28:29]
	v_cndmask_b32_e64 v25, v35, v25, s[6:7]
	v_cndmask_b32_e64 v24, v34, v24, s[6:7]
	s_nop 1
	v_mov_b32_dpp v34, v24 row_shr:4 row_mask:0xf bank_mask:0xf
	v_mov_b32_dpp v35, v25 row_shr:4 row_mask:0xf bank_mask:0xf
	v_cndmask_b32_e64 v29, v37, v29, s[6:7]
	v_cndmask_b32_e64 v28, v36, v28, s[6:7]
	s_nop 1
	v_mov_b32_dpp v36, v28 row_shr:4 row_mask:0xf bank_mask:0xf
	v_mov_b32_dpp v37, v29 row_shr:4 row_mask:0xf bank_mask:0xf
	s_waitcnt lgkmcnt(2)
	v_pk_mul_f32 v[34:35], v[24:25], v[34:35]
	v_mov_b32_dpp v33, v73 row_bcast:15 row_mask:0xa bank_mask:0xf
	v_cndmask_b32_e64 v35, v35, v25, s[8:9]
	v_cndmask_b32_e64 v34, v34, v24, s[8:9]
	s_nop 1
	v_mov_b32_dpp v60, v34 row_shr:8 row_mask:0xf bank_mask:0xf
	v_mov_b32_dpp v61, v35 row_shr:8 row_mask:0xf bank_mask:0xf
	s_waitcnt lgkmcnt(3)
	v_pk_fma_f32 v[36:37], v[24:25], v[36:37], v[28:29]
	v_mov_b32_dpp v38, v74 row_bcast:15 row_mask:0xa bank_mask:0xf
	v_cndmask_b32_e64 v37, v37, v29, s[8:9]
	v_cndmask_b32_e64 v36, v36, v28, s[8:9]
	s_waitcnt lgkmcnt(3)
	v_pk_mul_f32 v[28:29], v[72:73], v[32:33]
	s_waitcnt lgkmcnt(1)
	v_pk_mul_f32 v[32:33], v[34:35], v[60:61]
	v_mov_b32_dpp v60, v40 row_shr:1 row_mask:0xf bank_mask:0xf
	v_mov_b32_dpp v61, v41 row_shr:1 row_mask:0xf bank_mask:0xf
	v_mov_b32_dpp v39, v75 row_bcast:15 row_mask:0xa bank_mask:0xf
	v_mov_b32_dpp v62, v36 row_shr:8 row_mask:0xf bank_mask:0xf
	v_mov_b32_dpp v63, v37 row_shr:8 row_mask:0xf bank_mask:0xf
	v_cndmask_b32_e64 v79, v33, v35, s[10:11]
	v_cndmask_b32_e64 v78, v32, v34, s[10:11]
	s_waitcnt lgkmcnt(3)
	v_pk_fma_f32 v[32:33], v[86:87], v[60:61], v[40:41]
	v_cndmask_b32_e32 v31, v31, v87, vcc
	v_cndmask_b32_e32 v30, v30, v86, vcc
	v_cndmask_b32_e32 v33, v33, v41, vcc
	v_cndmask_b32_e32 v32, v32, v40, vcc
	s_waitcnt lgkmcnt(2)
	v_pk_fma_f32 v[24:25], v[72:73], v[38:39], v[74:75]
	s_waitcnt lgkmcnt(0)
	v_pk_fma_f32 v[38:39], v[34:35], v[62:63], v[36:37]
	v_mov_b32_dpp v34, v30 row_shr:2 row_mask:0xf bank_mask:0xf
	v_mov_b32_dpp v40, v32 row_shr:2 row_mask:0xf bank_mask:0xf
	v_mov_b32_dpp v35, v31 row_shr:2 row_mask:0xf bank_mask:0xf
	v_mov_b32_dpp v41, v33 row_shr:2 row_mask:0xf bank_mask:0xf
	v_cndmask_b32_e64 v77, v39, v37, s[10:11]
	v_cndmask_b32_e64 v76, v38, v36, s[10:11]
	v_mov_b32_dpp v36, v78 row_bcast:15 row_mask:0xa bank_mask:0xf
	s_waitcnt lgkmcnt(2)
	v_pk_mul_f32 v[34:35], v[30:31], v[34:35]
	s_waitcnt lgkmcnt(1)
	v_pk_fma_f32 v[38:39], v[30:31], v[40:41], v[32:33]
	v_cndmask_b32_e64 v35, v35, v31, s[6:7]
	v_cndmask_b32_e64 v34, v34, v30, s[6:7]
	v_cndmask_b32_e64 v33, v39, v33, s[6:7]
	v_cndmask_b32_e64 v32, v38, v32, s[6:7]
	v_mov_b32_dpp v37, v79 row_bcast:15 row_mask:0xa bank_mask:0xf
	v_mov_b32_dpp v38, v34 row_shr:4 row_mask:0xf bank_mask:0xf
	v_mov_b32_dpp v40, v32 row_shr:4 row_mask:0xf bank_mask:0xf
	v_mov_b32_dpp v39, v35 row_shr:4 row_mask:0xf bank_mask:0xf
	v_mov_b32_dpp v41, v33 row_shr:4 row_mask:0xf bank_mask:0xf
	s_waitcnt lgkmcnt(4)
	v_pk_mul_f32 v[30:31], v[78:79], v[36:37]
	v_pk_mul_f32 v[26:27], v[92:93], v[26:27]
	v_mov_b32_dpp v60, v76 row_bcast:15 row_mask:0xa bank_mask:0xf
	s_waitcnt lgkmcnt(2)
	v_pk_mul_f32 v[36:37], v[34:35], v[38:39]
	s_waitcnt lgkmcnt(1)
	v_pk_fma_f32 v[38:39], v[34:35], v[40:41], v[32:33]
	v_cndmask_b32_e64 v35, v37, v35, s[8:9]
	v_cndmask_b32_e64 v33, v39, v33, s[8:9]
	v_cndmask_b32_e64 v32, v38, v32, s[8:9]
	v_pk_mul_f32 v[38:39], v[42:43], v[90:91]
	v_cndmask_b32_e64 v34, v36, v34, s[8:9]
	v_pk_mul_f32 v[38:39], v[38:39], v[94:95]
	s_nop 1
	v_mov_b32_dpp v40, v38 row_shr:1 row_mask:0xf bank_mask:0xf
	v_mov_b32_dpp v41, v39 row_shr:1 row_mask:0xf bank_mask:0xf
	v_mov_b32_dpp v36, v34 row_shr:8 row_mask:0xf bank_mask:0xf
	v_mov_b32_dpp v37, v35 row_shr:8 row_mask:0xf bank_mask:0xf
	v_cndmask_b32_e32 v27, v27, v93, vcc
	v_cndmask_b32_e32 v26, v26, v92, vcc
	s_waitcnt lgkmcnt(2)
	v_pk_fma_f32 v[40:41], v[92:93], v[40:41], v[38:39]
	v_mov_b32_dpp v42, v32 row_shr:8 row_mask:0xf bank_mask:0xf
	v_cndmask_b32_e32 v39, v41, v39, vcc
	v_cndmask_b32_e32 v38, v40, v38, vcc
	v_mov_b32_dpp v43, v33 row_shr:8 row_mask:0xf bank_mask:0xf
	v_mov_b32_dpp v40, v26 row_shr:2 row_mask:0xf bank_mask:0xf
	v_mov_b32_dpp v62, v38 row_shr:2 row_mask:0xf bank_mask:0xf
	v_mov_b32_dpp v41, v27 row_shr:2 row_mask:0xf bank_mask:0xf
	v_mov_b32_dpp v63, v39 row_shr:2 row_mask:0xf bank_mask:0xf
	s_waitcnt lgkmcnt(6)
	v_pk_mul_f32 v[36:37], v[34:35], v[36:37]
	s_waitcnt lgkmcnt(4)
	v_pk_fma_f32 v[42:43], v[34:35], v[42:43], v[32:33]
	v_cndmask_b32_e64 v81, v37, v35, s[10:11]
	v_cndmask_b32_e64 v80, v36, v34, s[10:11]
	s_waitcnt lgkmcnt(1)
	v_pk_mul_f32 v[34:35], v[26:27], v[40:41]
	s_waitcnt lgkmcnt(0)
	v_pk_fma_f32 v[36:37], v[26:27], v[62:63], v[38:39]
	v_cndmask_b32_e64 v27, v35, v27, s[6:7]
	v_cndmask_b32_e64 v26, v34, v26, s[6:7]
	v_cndmask_b32_e64 v35, v37, v39, s[6:7]
	v_cndmask_b32_e64 v34, v36, v38, s[6:7]
	v_mov_b32_dpp v36, v26 row_shr:4 row_mask:0xf bank_mask:0xf
	s_nop 1
	v_mov_b32_dpp v38, v34 row_shr:4 row_mask:0xf bank_mask:0xf
	v_mov_b32_dpp v37, v27 row_shr:4 row_mask:0xf bank_mask:0xf
	v_mov_b32_dpp v39, v35 row_shr:4 row_mask:0xf bank_mask:0xf
	v_cndmask_b32_e64 v83, v43, v33, s[10:11]
	v_cndmask_b32_e64 v82, v42, v32, s[10:11]
	v_mov_b32_dpp v61, v77 row_bcast:15 row_mask:0xa bank_mask:0xf
	s_waitcnt lgkmcnt(2)
	v_pk_mul_f32 v[36:37], v[26:27], v[36:37]
	s_waitcnt lgkmcnt(1)
	v_pk_fma_f32 v[38:39], v[26:27], v[38:39], v[34:35]
	v_cndmask_b32_e64 v27, v37, v27, s[8:9]
	v_cndmask_b32_e64 v26, v36, v26, s[8:9]
	v_cndmask_b32_e64 v35, v39, v35, s[8:9]
	v_cndmask_b32_e64 v34, v38, v34, s[8:9]
	v_mov_b32_dpp v36, v26 row_shr:8 row_mask:0xf bank_mask:0xf
	s_nop 1
	v_mov_b32_dpp v38, v34 row_shr:8 row_mask:0xf bank_mask:0xf
	v_mov_b32_dpp v37, v27 row_shr:8 row_mask:0xf bank_mask:0xf
	v_mov_b32_dpp v39, v35 row_shr:8 row_mask:0xf bank_mask:0xf
	v_mov_b32_dpp v32, v80 row_bcast:15 row_mask:0xa bank_mask:0xf
	v_mov_b32_dpp v40, v82 row_bcast:15 row_mask:0xa bank_mask:0xf
	v_mov_b32_dpp v33, v81 row_bcast:15 row_mask:0xa bank_mask:0xf
	s_waitcnt lgkmcnt(4)
	v_pk_mul_f32 v[36:37], v[26:27], v[36:37]
	s_waitcnt lgkmcnt(3)
	v_pk_fma_f32 v[38:39], v[26:27], v[38:39], v[34:35]
	v_cndmask_b32_e64 v85, v37, v27, s[10:11]
	v_cndmask_b32_e64 v84, v36, v26, s[10:11]
	v_cndmask_b32_e64 v87, v39, v35, s[10:11]
	v_cndmask_b32_e64 v86, v38, v34, s[10:11]
	v_mov_b32_dpp v41, v83 row_bcast:15 row_mask:0xa bank_mask:0xf
	v_mov_b32_dpp v34, v84 row_bcast:15 row_mask:0xa bank_mask:0xf
	v_mov_b32_dpp v42, v86 row_bcast:15 row_mask:0xa bank_mask:0xf
	v_mov_b32_dpp v35, v85 row_bcast:15 row_mask:0xa bank_mask:0xf
	v_mov_b32_dpp v43, v87 row_bcast:15 row_mask:0xa bank_mask:0xf
	v_pk_fma_f32 v[26:27], v[78:79], v[60:61], v[76:77]
	s_waitcnt lgkmcnt(5)
	v_pk_mul_f32 v[36:37], v[80:81], v[32:33]
	s_waitcnt lgkmcnt(4)
	v_pk_fma_f32 v[32:33], v[80:81], v[40:41], v[82:83]
	s_waitcnt lgkmcnt(1)
	v_pk_mul_f32 v[38:39], v[84:85], v[34:35]
	s_waitcnt lgkmcnt(0)
	v_pk_fma_f32 v[34:35], v[84:85], v[42:43], v[86:87]
	v_pk_mul_f32 v[40:41], v[48:49], v[56:57]
	v_pk_mul_f32 v[48:49], v[96:97], v[158:159]
	v_pk_mul_f32 v[40:41], v[40:41], v[100:101]
	s_nop 1
	v_mov_b32_dpp v42, v40 row_shr:1 row_mask:0xf bank_mask:0xf
	v_mov_b32_dpp v43, v41 row_shr:1 row_mask:0xf bank_mask:0xf
	v_cndmask_b32_e32 v49, v49, v97, vcc
	v_cndmask_b32_e32 v48, v48, v96, vcc
	v_pk_mul_f32 v[50:51], v[50:51], v[58:59]
	v_pk_mul_f32 v[44:45], v[44:45], v[104:105]
	s_waitcnt lgkmcnt(0)
	v_pk_fma_f32 v[42:43], v[96:97], v[42:43], v[40:41]
	v_pk_mul_f32 v[50:51], v[50:51], v[102:103]
	v_cndmask_b32_e32 v41, v43, v41, vcc
	v_cndmask_b32_e32 v40, v42, v40, vcc
	v_mov_b32_dpp v42, v48 row_shr:2 row_mask:0xf bank_mask:0xf
	v_mov_b32_dpp v43, v49 row_shr:2 row_mask:0xf bank_mask:0xf
	v_mov_b32_dpp v56, v40 row_shr:2 row_mask:0xf bank_mask:0xf
	v_mov_b32_dpp v57, v41 row_shr:2 row_mask:0xf bank_mask:0xf
	v_mov_b32_dpp v58, v50 row_shr:1 row_mask:0xf bank_mask:0xf
	v_mov_b32_dpp v59, v51 row_shr:1 row_mask:0xf bank_mask:0xf
	s_waitcnt lgkmcnt(4)
	v_pk_mul_f32 v[42:43], v[48:49], v[42:43]
	v_pk_mul_f32 v[44:45], v[44:45], v[106:107]
	s_waitcnt lgkmcnt(2)
	v_pk_fma_f32 v[56:57], v[48:49], v[56:57], v[40:41]
	v_cndmask_b32_e64 v43, v43, v49, s[6:7]
	v_cndmask_b32_e64 v42, v42, v48, s[6:7]
	v_cndmask_b32_e64 v41, v57, v41, s[6:7]
	v_cndmask_b32_e64 v40, v56, v40, s[6:7]
	v_mov_b32_dpp v48, v42 row_shr:4 row_mask:0xf bank_mask:0xf
	v_mov_b32_dpp v49, v43 row_shr:4 row_mask:0xf bank_mask:0xf
	v_mov_b32_dpp v56, v40 row_shr:4 row_mask:0xf bank_mask:0xf
	v_mov_b32_dpp v57, v41 row_shr:4 row_mask:0xf bank_mask:0xf
	v_pk_mul_f32 v[46:47], v[46:47], v[108:109]
	v_pk_mul_f32 v[62:63], v[54:55], v[152:153]
	s_waitcnt lgkmcnt(2)
	v_pk_mul_f32 v[48:49], v[42:43], v[48:49]
	v_pk_mul_f32 v[46:47], v[46:47], v[110:111]
	s_waitcnt lgkmcnt(0)
	v_pk_fma_f32 v[56:57], v[42:43], v[56:57], v[40:41]
	v_cndmask_b32_e64 v43, v49, v43, s[8:9]
	v_cndmask_b32_e64 v42, v48, v42, s[8:9]
	s_nop 1
	v_mov_b32_dpp v48, v42 row_shr:8 row_mask:0xf bank_mask:0xf
	v_mov_b32_dpp v49, v43 row_shr:8 row_mask:0xf bank_mask:0xf
	v_cndmask_b32_e64 v41, v57, v41, s[8:9]
	v_cndmask_b32_e64 v40, v56, v40, s[8:9]
	s_nop 1
	v_mov_b32_dpp v56, v40 row_shr:8 row_mask:0xf bank_mask:0xf
	v_mov_b32_dpp v57, v41 row_shr:8 row_mask:0xf bank_mask:0xf
	s_waitcnt lgkmcnt(2)
	v_pk_mul_f32 v[48:49], v[42:43], v[48:49]
	s_waitcnt lgkmcnt(0)
	v_pk_fma_f32 v[56:57], v[42:43], v[56:57], v[40:41]
	v_cndmask_b32_e64 v89, v49, v43, s[10:11]
	v_cndmask_b32_e64 v88, v48, v42, s[10:11]
	v_pk_mul_f32 v[42:43], v[98:99], v[156:157]
	v_pk_fma_f32 v[48:49], v[98:99], v[58:59], v[50:51]
	v_cndmask_b32_e32 v43, v43, v99, vcc
	v_cndmask_b32_e32 v42, v42, v98, vcc
	v_cndmask_b32_e32 v49, v49, v51, vcc
	v_cndmask_b32_e32 v48, v48, v50, vcc
	v_mov_b32_dpp v50, v42 row_shr:2 row_mask:0xf bank_mask:0xf
	s_nop 1
	v_mov_b32_dpp v58, v48 row_shr:2 row_mask:0xf bank_mask:0xf
	v_mov_b32_dpp v51, v43 row_shr:2 row_mask:0xf bank_mask:0xf
	v_mov_b32_dpp v59, v49 row_shr:2 row_mask:0xf bank_mask:0xf
	v_cndmask_b32_e64 v91, v57, v41, s[10:11]
	v_cndmask_b32_e64 v90, v56, v40, s[10:11]
	v_mov_b32_dpp v40, v88 row_bcast:15 row_mask:0xa bank_mask:0xf
	s_waitcnt lgkmcnt(2)
	v_pk_mul_f32 v[50:51], v[42:43], v[50:51]
	s_waitcnt lgkmcnt(1)
	v_pk_fma_f32 v[56:57], v[42:43], v[58:59], v[48:49]
	v_cndmask_b32_e64 v43, v51, v43, s[6:7]
	v_cndmask_b32_e64 v42, v50, v42, s[6:7]
	v_cndmask_b32_e64 v49, v57, v49, s[6:7]
	v_cndmask_b32_e64 v48, v56, v48, s[6:7]
	v_mov_b32_dpp v50, v42 row_shr:4 row_mask:0xf bank_mask:0xf
	s_nop 1
	v_mov_b32_dpp v56, v48 row_shr:4 row_mask:0xf bank_mask:0xf
	v_mov_b32_dpp v51, v43 row_shr:4 row_mask:0xf bank_mask:0xf
	v_mov_b32_dpp v57, v49 row_shr:4 row_mask:0xf bank_mask:0xf
	v_mov_b32_dpp v58, v90 row_bcast:15 row_mask:0xa bank_mask:0xf
	v_mov_b32_dpp v41, v89 row_bcast:15 row_mask:0xa bank_mask:0xf
	v_mov_b32_dpp v59, v91 row_bcast:15 row_mask:0xa bank_mask:0xf
	s_waitcnt lgkmcnt(4)
	v_pk_mul_f32 v[50:51], v[42:43], v[50:51]
	s_waitcnt lgkmcnt(3)
	v_pk_fma_f32 v[56:57], v[42:43], v[56:57], v[48:49]
	v_cndmask_b32_e64 v43, v51, v43, s[8:9]
	v_cndmask_b32_e64 v42, v50, v42, s[8:9]
	v_cndmask_b32_e64 v51, v57, v49, s[8:9]
	v_cndmask_b32_e64 v50, v56, v48, s[8:9]
	s_nop 1
	v_mov_b32_dpp v60, v50 row_shr:8 row_mask:0xf bank_mask:0xf
	v_mov_b32_dpp v61, v51 row_shr:8 row_mask:0xf bank_mask:0xf
	v_mov_b32_dpp v56, v42 row_shr:8 row_mask:0xf bank_mask:0xf
	v_mov_b32_dpp v57, v43 row_shr:8 row_mask:0xf bank_mask:0xf
	s_waitcnt lgkmcnt(5)
	v_pk_mul_f32 v[48:49], v[88:89], v[40:41]
	s_waitcnt lgkmcnt(4)
	v_pk_fma_f32 v[40:41], v[88:89], v[58:59], v[90:91]
	s_waitcnt lgkmcnt(2)
	v_pk_fma_f32 v[58:59], v[42:43], v[60:61], v[50:51]
	v_mov_b32_dpp v60, v44 row_shr:1 row_mask:0xf bank_mask:0xf
	v_mov_b32_dpp v61, v45 row_shr:1 row_mask:0xf bank_mask:0xf
	s_waitcnt lgkmcnt(2)
	v_pk_mul_f32 v[56:57], v[42:43], v[56:57]
	v_cndmask_b32_e64 v93, v59, v51, s[10:11]
	v_cndmask_b32_e64 v95, v57, v43, s[10:11]
	v_cndmask_b32_e64 v94, v56, v42, s[10:11]
	s_waitcnt lgkmcnt(0)
	v_pk_fma_f32 v[56:57], v[52:53], v[60:61], v[44:45]
	v_pk_mul_f32 v[42:43], v[52:53], v[154:155]
	v_cndmask_b32_e32 v45, v57, v45, vcc
	v_cndmask_b32_e32 v44, v56, v44, vcc
	s_nop 1
	v_mov_b32_dpp v56, v44 row_shr:2 row_mask:0xf bank_mask:0xf
	v_mov_b32_dpp v57, v45 row_shr:2 row_mask:0xf bank_mask:0xf
	v_cndmask_b32_e32 v43, v43, v53, vcc
	v_cndmask_b32_e32 v42, v42, v52, vcc
	s_nop 1
	v_mov_b32_dpp v52, v42 row_shr:2 row_mask:0xf bank_mask:0xf
	v_mov_b32_dpp v53, v43 row_shr:2 row_mask:0xf bank_mask:0xf
	s_waitcnt lgkmcnt(2)
	v_pk_fma_f32 v[56:57], v[42:43], v[56:57], v[44:45]
	v_cndmask_b32_e64 v92, v58, v50, s[10:11]
	v_cndmask_b32_e64 v45, v57, v45, s[6:7]
	v_cndmask_b32_e64 v44, v56, v44, s[6:7]
	s_nop 1
	v_mov_b32_dpp v56, v44 row_shr:4 row_mask:0xf bank_mask:0xf
	v_mov_b32_dpp v57, v45 row_shr:4 row_mask:0xf bank_mask:0xf
	s_waitcnt lgkmcnt(2)
	v_pk_mul_f32 v[52:53], v[42:43], v[52:53]
	v_mov_b32_dpp v50, v94 row_bcast:15 row_mask:0xa bank_mask:0xf
	v_cndmask_b32_e64 v43, v53, v43, s[6:7]
	v_cndmask_b32_e64 v42, v52, v42, s[6:7]
	s_nop 1
	v_mov_b32_dpp v52, v42 row_shr:4 row_mask:0xf bank_mask:0xf
	v_mov_b32_dpp v53, v43 row_shr:4 row_mask:0xf bank_mask:0xf
	s_waitcnt lgkmcnt(3)
	v_pk_fma_f32 v[56:57], v[42:43], v[56:57], v[44:45]
	v_mov_b32_dpp v51, v95 row_bcast:15 row_mask:0xa bank_mask:0xf
	v_cndmask_b32_e64 v45, v57, v45, s[8:9]
	v_cndmask_b32_e64 v44, v56, v44, s[8:9]
	v_mov_b32_dpp v56, v46 row_shr:1 row_mask:0xf bank_mask:0xf
	v_mov_b32_dpp v57, v47 row_shr:1 row_mask:0xf bank_mask:0xf
	s_waitcnt lgkmcnt(3)
	v_pk_mul_f32 v[52:53], v[42:43], v[52:53]
	v_mov_b32_dpp v60, v44 row_shr:8 row_mask:0xf bank_mask:0xf
	v_cndmask_b32_e64 v43, v53, v43, s[8:9]
	v_cndmask_b32_e64 v42, v52, v42, s[8:9]
	s_waitcnt lgkmcnt(1)
	v_pk_fma_f32 v[56:57], v[54:55], v[56:57], v[46:47]
	v_mov_b32_dpp v52, v42 row_shr:8 row_mask:0xf bank_mask:0xf
	v_mov_b32_dpp v53, v43 row_shr:8 row_mask:0xf bank_mask:0xf
	v_cndmask_b32_e32 v55, v63, v55, vcc
	v_cndmask_b32_e32 v54, v62, v54, vcc
	v_cndmask_b32_e32 v47, v57, v47, vcc
	v_cndmask_b32_e32 v46, v56, v46, vcc
	v_mov_b32_dpp v61, v45 row_shr:8 row_mask:0xf bank_mask:0xf
	v_mov_b32_dpp v56, v54 row_shr:2 row_mask:0xf bank_mask:0xf
	v_mov_b32_dpp v62, v46 row_shr:2 row_mask:0xf bank_mask:0xf
	v_mov_b32_dpp v57, v55 row_shr:2 row_mask:0xf bank_mask:0xf
	v_mov_b32_dpp v63, v47 row_shr:2 row_mask:0xf bank_mask:0xf
	s_waitcnt lgkmcnt(5)
	v_pk_mul_f32 v[52:53], v[42:43], v[52:53]
	s_waitcnt lgkmcnt(4)
	v_pk_fma_f32 v[60:61], v[42:43], v[60:61], v[44:45]
	v_cndmask_b32_e64 v97, v53, v43, s[10:11]
	v_cndmask_b32_e64 v96, v52, v42, s[10:11]
	s_waitcnt lgkmcnt(1)
	v_pk_mul_f32 v[42:43], v[54:55], v[56:57]
	s_waitcnt lgkmcnt(0)
	v_pk_fma_f32 v[52:53], v[54:55], v[62:63], v[46:47]
	v_cndmask_b32_e64 v43, v43, v55, s[6:7]
	v_cndmask_b32_e64 v42, v42, v54, s[6:7]
	v_cndmask_b32_e64 v47, v53, v47, s[6:7]
	v_cndmask_b32_e64 v46, v52, v46, s[6:7]
	v_mov_b32_dpp v52, v42 row_shr:4 row_mask:0xf bank_mask:0xf
	s_nop 1
	v_mov_b32_dpp v54, v46 row_shr:4 row_mask:0xf bank_mask:0xf
	v_mov_b32_dpp v53, v43 row_shr:4 row_mask:0xf bank_mask:0xf
	v_mov_b32_dpp v55, v47 row_shr:4 row_mask:0xf bank_mask:0xf
	v_cndmask_b32_e64 v99, v61, v45, s[10:11]
	v_cndmask_b32_e64 v98, v60, v44, s[10:11]
	v_mov_b32_dpp v58, v92 row_bcast:15 row_mask:0xa bank_mask:0xf
	s_waitcnt lgkmcnt(2)
	v_pk_mul_f32 v[52:53], v[42:43], v[52:53]
	s_waitcnt lgkmcnt(1)
	v_pk_fma_f32 v[54:55], v[42:43], v[54:55], v[46:47]
	v_cndmask_b32_e64 v43, v53, v43, s[8:9]
	v_cndmask_b32_e64 v42, v52, v42, s[8:9]
	v_cndmask_b32_e64 v47, v55, v47, s[8:9]
	v_cndmask_b32_e64 v46, v54, v46, s[8:9]
	v_mov_b32_dpp v52, v42 row_shr:8 row_mask:0xf bank_mask:0xf
	s_nop 1
	v_mov_b32_dpp v54, v46 row_shr:8 row_mask:0xf bank_mask:0xf
	v_mov_b32_dpp v53, v43 row_shr:8 row_mask:0xf bank_mask:0xf
	v_mov_b32_dpp v55, v47 row_shr:8 row_mask:0xf bank_mask:0xf
	v_mov_b32_dpp v59, v93 row_bcast:15 row_mask:0xa bank_mask:0xf
	v_mov_b32_dpp v44, v96 row_bcast:15 row_mask:0xa bank_mask:0xf
	v_mov_b32_dpp v56, v98 row_bcast:15 row_mask:0xa bank_mask:0xf
	s_waitcnt lgkmcnt(4)
	v_pk_mul_f32 v[52:53], v[42:43], v[52:53]
	s_waitcnt lgkmcnt(3)
	v_pk_fma_f32 v[54:55], v[42:43], v[54:55], v[46:47]
	v_cndmask_b32_e64 v101, v53, v43, s[10:11]
	v_cndmask_b32_e64 v100, v52, v42, s[10:11]
	v_cndmask_b32_e64 v103, v55, v47, s[10:11]
	v_cndmask_b32_e64 v102, v54, v46, s[10:11]
	v_mov_b32_dpp v45, v97 row_bcast:15 row_mask:0xa bank_mask:0xf
	v_mov_b32_dpp v57, v99 row_bcast:15 row_mask:0xa bank_mask:0xf
	v_mov_b32_dpp v46, v100 row_bcast:15 row_mask:0xa bank_mask:0xf
	v_mov_b32_dpp v60, v102 row_bcast:15 row_mask:0xa bank_mask:0xf
	v_mov_b32_dpp v47, v101 row_bcast:15 row_mask:0xa bank_mask:0xf
	v_mov_b32_dpp v61, v103 row_bcast:15 row_mask:0xa bank_mask:0xf
	v_pk_mul_f32 v[50:51], v[94:95], v[50:51]
	s_waitcnt lgkmcnt(8)
	v_pk_fma_f32 v[42:43], v[94:95], v[58:59], v[92:93]
	s_waitcnt lgkmcnt(5)
	v_pk_mul_f32 v[52:53], v[96:97], v[44:45]
	s_waitcnt lgkmcnt(4)
	v_pk_fma_f32 v[44:45], v[96:97], v[56:57], v[98:99]
	s_waitcnt lgkmcnt(1)
	v_pk_mul_f32 v[54:55], v[100:101], v[46:47]
	s_waitcnt lgkmcnt(0)
	v_pk_fma_f32 v[46:47], v[100:101], v[60:61], v[102:103]
	v_pk_mul_f32 v[0:1], v[0:1], v[112:113]
	v_pk_mul_f32 v[58:59], v[116:117], v[150:151]
	v_pk_mul_f32 v[0:1], v[0:1], v[120:121]
	s_nop 1
	v_mov_b32_dpp v56, v0 row_shr:1 row_mask:0xf bank_mask:0xf
	v_mov_b32_dpp v57, v1 row_shr:1 row_mask:0xf bank_mask:0xf
	v_cndmask_b32_e32 v59, v59, v117, vcc
	v_cndmask_b32_e32 v58, v58, v116, vcc
	v_pk_mul_f32 v[2:3], v[2:3], v[114:115]
	v_pk_mul_f32 v[4:5], v[4:5], v[124:125]
	s_waitcnt lgkmcnt(0)
	v_pk_fma_f32 v[56:57], v[116:117], v[56:57], v[0:1]
	v_pk_mul_f32 v[2:3], v[2:3], v[122:123]
	v_cndmask_b32_e32 v1, v57, v1, vcc
	v_cndmask_b32_e32 v0, v56, v0, vcc
	v_mov_b32_dpp v56, v58 row_shr:2 row_mask:0xf bank_mask:0xf
	v_mov_b32_dpp v57, v59 row_shr:2 row_mask:0xf bank_mask:0xf
	v_mov_b32_dpp v60, v0 row_shr:2 row_mask:0xf bank_mask:0xf
	v_mov_b32_dpp v61, v1 row_shr:2 row_mask:0xf bank_mask:0xf
	v_mov_b32_dpp v62, v2 row_shr:1 row_mask:0xf bank_mask:0xf
	v_mov_b32_dpp v63, v3 row_shr:1 row_mask:0xf bank_mask:0xf
	s_waitcnt lgkmcnt(4)
	v_pk_mul_f32 v[56:57], v[58:59], v[56:57]
	v_pk_mul_f32 v[4:5], v[4:5], v[128:129]
	s_waitcnt lgkmcnt(2)
	v_pk_fma_f32 v[60:61], v[58:59], v[60:61], v[0:1]
	v_cndmask_b32_e64 v57, v57, v59, s[6:7]
	v_cndmask_b32_e64 v56, v56, v58, s[6:7]
	v_cndmask_b32_e64 v1, v61, v1, s[6:7]
	v_cndmask_b32_e64 v0, v60, v0, s[6:7]
	v_mov_b32_dpp v58, v56 row_shr:4 row_mask:0xf bank_mask:0xf
	v_mov_b32_dpp v59, v57 row_shr:4 row_mask:0xf bank_mask:0xf
	v_mov_b32_dpp v60, v0 row_shr:4 row_mask:0xf bank_mask:0xf
	v_mov_b32_dpp v61, v1 row_shr:4 row_mask:0xf bank_mask:0xf
	v_mov_b32_dpp v112, v4 row_shr:1 row_mask:0xf bank_mask:0xf
	v_mov_b32_dpp v113, v5 row_shr:1 row_mask:0xf bank_mask:0xf
	s_waitcnt lgkmcnt(4)
	v_pk_mul_f32 v[58:59], v[56:57], v[58:59]
	v_pk_mul_f32 v[6:7], v[6:7], v[130:131]
	s_waitcnt lgkmcnt(2)
	v_pk_fma_f32 v[60:61], v[56:57], v[60:61], v[0:1]
	v_cndmask_b32_e64 v57, v59, v57, s[8:9]
	v_cndmask_b32_e64 v56, v58, v56, s[8:9]
	s_nop 1
	v_mov_b32_dpp v58, v56 row_shr:8 row_mask:0xf bank_mask:0xf
	v_mov_b32_dpp v59, v57 row_shr:8 row_mask:0xf bank_mask:0xf
	v_cndmask_b32_e64 v1, v61, v1, s[8:9]
	v_cndmask_b32_e64 v0, v60, v0, s[8:9]
	s_nop 1
	v_mov_b32_dpp v60, v0 row_shr:8 row_mask:0xf bank_mask:0xf
	v_mov_b32_dpp v61, v1 row_shr:8 row_mask:0xf bank_mask:0xf
	s_waitcnt lgkmcnt(2)
	v_pk_mul_f32 v[58:59], v[56:57], v[58:59]
	v_pk_mul_f32 v[6:7], v[6:7], v[134:135]
	v_cndmask_b32_e64 v105, v59, v57, s[10:11]
	v_cndmask_b32_e64 v104, v58, v56, s[10:11]
	s_waitcnt lgkmcnt(0)
	v_pk_fma_f32 v[60:61], v[56:57], v[60:61], v[0:1]
	v_pk_mul_f32 v[56:57], v[118:119], v[148:149]
	v_pk_fma_f32 v[58:59], v[118:119], v[62:63], v[2:3]
	v_cndmask_b32_e32 v57, v57, v119, vcc
	v_cndmask_b32_e32 v56, v56, v118, vcc
	v_cndmask_b32_e32 v3, v59, v3, vcc
	v_cndmask_b32_e32 v2, v58, v2, vcc
	v_mov_b32_dpp v58, v56 row_shr:2 row_mask:0xf bank_mask:0xf
	v_mov_b32_dpp v59, v57 row_shr:2 row_mask:0xf bank_mask:0xf
	v_mov_b32_dpp v62, v2 row_shr:2 row_mask:0xf bank_mask:0xf
	v_mov_b32_dpp v63, v3 row_shr:2 row_mask:0xf bank_mask:0xf
	v_cndmask_b32_e64 v107, v61, v1, s[10:11]
	v_cndmask_b32_e64 v106, v60, v0, s[10:11]
	s_waitcnt lgkmcnt(2)
	v_pk_mul_f32 v[58:59], v[56:57], v[58:59]
	v_mov_b32_dpp v0, v104 row_bcast:15 row_mask:0xa bank_mask:0xf
	s_waitcnt lgkmcnt(1)
	v_pk_fma_f32 v[60:61], v[56:57], v[62:63], v[2:3]
	v_cndmask_b32_e64 v57, v59, v57, s[6:7]
	v_cndmask_b32_e64 v56, v58, v56, s[6:7]
	v_cndmask_b32_e64 v3, v61, v3, s[6:7]
	v_cndmask_b32_e64 v2, v60, v2, s[6:7]
	v_mov_b32_dpp v58, v56 row_shr:4 row_mask:0xf bank_mask:0xf
	v_mov_b32_dpp v59, v57 row_shr:4 row_mask:0xf bank_mask:0xf
	v_mov_b32_dpp v60, v2 row_shr:4 row_mask:0xf bank_mask:0xf
	v_mov_b32_dpp v61, v3 row_shr:4 row_mask:0xf bank_mask:0xf
	v_mov_b32_dpp v62, v106 row_bcast:15 row_mask:0xa bank_mask:0xf
	v_mov_b32_dpp v1, v105 row_bcast:15 row_mask:0xa bank_mask:0xf
	s_waitcnt lgkmcnt(4)
	v_pk_mul_f32 v[58:59], v[56:57], v[58:59]
	v_mov_b32_dpp v63, v107 row_bcast:15 row_mask:0xa bank_mask:0xf
	s_waitcnt lgkmcnt(3)
	v_pk_fma_f32 v[60:61], v[56:57], v[60:61], v[2:3]
	v_cndmask_b32_e64 v59, v59, v57, s[8:9]
	v_cndmask_b32_e64 v58, v58, v56, s[8:9]
	v_cndmask_b32_e64 v3, v61, v3, s[8:9]
	v_cndmask_b32_e64 v2, v60, v2, s[8:9]
	v_mov_b32_dpp v60, v58 row_shr:8 row_mask:0xf bank_mask:0xf
	v_mov_b32_dpp v61, v59 row_shr:8 row_mask:0xf bank_mask:0xf
	v_mov_b32_dpp v108, v2 row_shr:8 row_mask:0xf bank_mask:0xf
	v_mov_b32_dpp v109, v3 row_shr:8 row_mask:0xf bank_mask:0xf
	s_waitcnt lgkmcnt(5)
	v_pk_mul_f32 v[56:57], v[104:105], v[0:1]
	s_waitcnt lgkmcnt(4)
	v_pk_fma_f32 v[0:1], v[104:105], v[62:63], v[106:107]
	s_waitcnt lgkmcnt(2)
	v_pk_mul_f32 v[60:61], v[58:59], v[60:61]
	v_pk_mul_f32 v[114:115], v[132:133], v[136:137]
	s_waitcnt lgkmcnt(0)
	v_pk_fma_f32 v[62:63], v[58:59], v[108:109], v[2:3]
	v_cndmask_b32_e64 v111, v61, v59, s[10:11]
	v_cndmask_b32_e64 v110, v60, v58, s[10:11]
	v_pk_mul_f32 v[58:59], v[126:127], v[146:147]
	v_pk_fma_f32 v[60:61], v[126:127], v[112:113], v[4:5]
	v_cndmask_b32_e32 v59, v59, v127, vcc
	v_cndmask_b32_e32 v58, v58, v126, vcc
	v_cndmask_b32_e32 v5, v61, v5, vcc
	v_cndmask_b32_e32 v4, v60, v4, vcc
	v_mov_b32_dpp v60, v58 row_shr:2 row_mask:0xf bank_mask:0xf
	s_nop 1
	v_mov_b32_dpp v112, v4 row_shr:2 row_mask:0xf bank_mask:0xf
	v_mov_b32_dpp v61, v59 row_shr:2 row_mask:0xf bank_mask:0xf
	v_mov_b32_dpp v113, v5 row_shr:2 row_mask:0xf bank_mask:0xf
	v_cndmask_b32_e64 v109, v63, v3, s[10:11]
	v_cndmask_b32_e64 v108, v62, v2, s[10:11]
	v_mov_b32_dpp v2, v110 row_bcast:15 row_mask:0xa bank_mask:0xf
	s_waitcnt lgkmcnt(2)
	v_pk_mul_f32 v[60:61], v[58:59], v[60:61]
	s_waitcnt lgkmcnt(1)
	v_pk_fma_f32 v[62:63], v[58:59], v[112:113], v[4:5]
	v_cndmask_b32_e64 v61, v61, v59, s[6:7]
	v_cndmask_b32_e64 v60, v60, v58, s[6:7]
	v_cndmask_b32_e64 v5, v63, v5, s[6:7]
	v_cndmask_b32_e64 v4, v62, v4, s[6:7]
	v_mov_b32_dpp v3, v111 row_bcast:15 row_mask:0xa bank_mask:0xf
	v_mov_b32_dpp v62, v60 row_shr:4 row_mask:0xf bank_mask:0xf
	v_mov_b32_dpp v112, v4 row_shr:4 row_mask:0xf bank_mask:0xf
	v_mov_b32_dpp v63, v61 row_shr:4 row_mask:0xf bank_mask:0xf
	v_mov_b32_dpp v113, v5 row_shr:4 row_mask:0xf bank_mask:0xf
	s_waitcnt lgkmcnt(4)
	v_pk_mul_f32 v[58:59], v[110:111], v[2:3]
	v_cndmask_b32_e32 v115, v115, v133, vcc
	v_cndmask_b32_e32 v114, v114, v132, vcc
	s_waitcnt lgkmcnt(1)
	v_pk_mul_f32 v[2:3], v[60:61], v[62:63]
	s_waitcnt lgkmcnt(0)
	v_pk_fma_f32 v[62:63], v[60:61], v[112:113], v[4:5]
	v_cndmask_b32_e64 v3, v3, v61, s[8:9]
	v_cndmask_b32_e64 v5, v63, v5, s[8:9]
	v_cndmask_b32_e64 v4, v62, v4, s[8:9]
	v_mov_b32_dpp v62, v6 row_shr:1 row_mask:0xf bank_mask:0xf
	v_mov_b32_dpp v63, v7 row_shr:1 row_mask:0xf bank_mask:0xf
	v_cndmask_b32_e64 v2, v2, v60, s[8:9]
	s_nop 1
	v_mov_b32_dpp v60, v2 row_shr:8 row_mask:0xf bank_mask:0xf
	v_mov_b32_dpp v61, v3 row_shr:8 row_mask:0xf bank_mask:0xf
	v_mov_b32_dpp v112, v4 row_shr:8 row_mask:0xf bank_mask:0xf
	s_waitcnt lgkmcnt(3)
	v_pk_fma_f32 v[62:63], v[132:133], v[62:63], v[6:7]
	v_mov_b32_dpp v113, v5 row_shr:8 row_mask:0xf bank_mask:0xf
	v_cndmask_b32_e32 v7, v63, v7, vcc
	v_cndmask_b32_e32 v6, v62, v6, vcc
	v_mov_b32_dpp v62, v114 row_shr:2 row_mask:0xf bank_mask:0xf
	s_nop 1
	v_mov_b32_dpp v116, v6 row_shr:2 row_mask:0xf bank_mask:0xf
	v_mov_b32_dpp v63, v115 row_shr:2 row_mask:0xf bank_mask:0xf
	v_mov_b32_dpp v117, v7 row_shr:2 row_mask:0xf bank_mask:0xf
	s_waitcnt lgkmcnt(6)
	v_pk_mul_f32 v[60:61], v[2:3], v[60:61]
	s_waitcnt lgkmcnt(4)
	v_pk_fma_f32 v[118:119], v[2:3], v[112:113], v[4:5]
	v_cndmask_b32_e64 v113, v61, v3, s[10:11]
	v_cndmask_b32_e64 v112, v60, v2, s[10:11]
	s_waitcnt lgkmcnt(1)
	v_pk_mul_f32 v[2:3], v[114:115], v[62:63]
	s_waitcnt lgkmcnt(0)
	v_pk_fma_f32 v[60:61], v[114:115], v[116:117], v[6:7]
	v_cndmask_b32_e64 v3, v3, v115, s[6:7]
	v_cndmask_b32_e64 v2, v2, v114, s[6:7]
	v_cndmask_b32_e64 v7, v61, v7, s[6:7]
	v_cndmask_b32_e64 v6, v60, v6, s[6:7]
	v_mov_b32_dpp v60, v2 row_shr:4 row_mask:0xf bank_mask:0xf
	s_nop 1
	v_mov_b32_dpp v62, v6 row_shr:4 row_mask:0xf bank_mask:0xf
	v_mov_b32_dpp v61, v3 row_shr:4 row_mask:0xf bank_mask:0xf
	v_mov_b32_dpp v63, v7 row_shr:4 row_mask:0xf bank_mask:0xf
	v_cndmask_b32_e64 v115, v119, v5, s[10:11]
	v_cndmask_b32_e64 v114, v118, v4, s[10:11]
	v_mov_b32_dpp v120, v108 row_bcast:15 row_mask:0xa bank_mask:0xf
	s_waitcnt lgkmcnt(2)
	v_pk_mul_f32 v[60:61], v[2:3], v[60:61]
	s_waitcnt lgkmcnt(1)
	v_pk_fma_f32 v[62:63], v[2:3], v[62:63], v[6:7]
	v_cndmask_b32_e64 v3, v61, v3, s[8:9]
	v_cndmask_b32_e64 v2, v60, v2, s[8:9]
	v_cndmask_b32_e64 v7, v63, v7, s[8:9]
	v_cndmask_b32_e64 v6, v62, v6, s[8:9]
	v_mov_b32_dpp v60, v2 row_shr:8 row_mask:0xf bank_mask:0xf
	s_nop 1
	v_mov_b32_dpp v62, v6 row_shr:8 row_mask:0xf bank_mask:0xf
	v_mov_b32_dpp v61, v3 row_shr:8 row_mask:0xf bank_mask:0xf
	v_mov_b32_dpp v63, v7 row_shr:8 row_mask:0xf bank_mask:0xf
	v_mov_b32_dpp v121, v109 row_bcast:15 row_mask:0xa bank_mask:0xf
	v_mov_b32_dpp v4, v112 row_bcast:15 row_mask:0xa bank_mask:0xf
	v_mov_b32_dpp v122, v114 row_bcast:15 row_mask:0xa bank_mask:0xf
	s_waitcnt lgkmcnt(4)
	v_pk_mul_f32 v[60:61], v[2:3], v[60:61]
	s_waitcnt lgkmcnt(3)
	v_pk_fma_f32 v[62:63], v[2:3], v[62:63], v[6:7]
	v_cndmask_b32_e64 v117, v61, v3, s[10:11]
	v_cndmask_b32_e64 v116, v60, v2, s[10:11]
	v_cndmask_b32_e64 v119, v63, v7, s[10:11]
	v_cndmask_b32_e64 v118, v62, v6, s[10:11]
	v_mov_b32_dpp v5, v113 row_bcast:15 row_mask:0xa bank_mask:0xf
	v_mov_b32_dpp v123, v115 row_bcast:15 row_mask:0xa bank_mask:0xf
	v_mov_b32_dpp v6, v116 row_bcast:15 row_mask:0xa bank_mask:0xf
	v_mov_b32_dpp v124, v118 row_bcast:15 row_mask:0xa bank_mask:0xf
	v_mov_b32_dpp v7, v117 row_bcast:15 row_mask:0xa bank_mask:0xf
	v_mov_b32_dpp v125, v119 row_bcast:15 row_mask:0xa bank_mask:0xf
	s_waitcnt lgkmcnt(8)
	v_pk_fma_f32 v[2:3], v[110:111], v[120:121], v[108:109]
	s_waitcnt lgkmcnt(5)
	v_pk_mul_f32 v[60:61], v[112:113], v[4:5]
	s_waitcnt lgkmcnt(4)
	v_pk_fma_f32 v[4:5], v[112:113], v[122:123], v[114:115]
	s_waitcnt lgkmcnt(1)
	v_pk_mul_f32 v[62:63], v[116:117], v[6:7]
	s_waitcnt lgkmcnt(0)
	v_pk_fma_f32 v[6:7], v[116:117], v[124:125], v[118:119]
	v_cmp_eq_u32_e64 s[6:7], 31, v162
	v_and_b32_e32 v122, 0xffffffc0, v160
	s_and_saveexec_b64 s[2:3], s[6:7]
	s_cbranch_execz .LBB0_906
	v_or_b32_e32 v120, v164, v122
	v_lshl_add_u32 v120, v120, 2, s89
	ds_write_b128 v120, v[8:11] offset:34816
	ds_write_b128 v120, v[12:15] offset:35840
	ds_write_b128 v120, v[20:23] offset:34848
	ds_write_b128 v120, v[16:19] offset:35872
	ds_write_b128 v120, v[28:31] offset:34880
	ds_write_b128 v120, v[24:27] offset:35904
	ds_write_b128 v120, v[36:39] offset:34912
	ds_write_b128 v120, v[32:35] offset:35936
	ds_write_b128 v120, v[48:51] offset:34944
	ds_write_b128 v120, v[40:43] offset:35968
	ds_write_b128 v120, v[52:55] offset:34976
	ds_write_b128 v120, v[44:47] offset:36000
	ds_write_b128 v120, v[56:59] offset:35008
	ds_write_b128 v120, v[0:3] offset:36032
	ds_write_b128 v120, v[60:63] offset:35040
	ds_write_b128 v120, v[4:7] offset:36064
